# attention: hand-written staggered tile loops, line-granular KV staging, static unit order
# speedup vs baseline: 1.0183x; 1.0183x over previous
; #define LAS __attribute__((address_space(3)))
; template <int DV, int NMAP>
; __device__ __forceinline__ void attn_unit(LAS unsigned char* lds, const bf16_t* U, bf16_t* MIX, const float* logf, int b, int h, int qb, float lam, float slope2, const float* gn, float outscale, const int tid) {
;     ...
;             float incl = 0.f, wsum = 0.f;
; #pragma unroll
;             for (int j4 = 0; j4 < 16; ++j4) { const f32x4 t = *(const LAS f32x4*)(tots + wid * 64 + 4 * j4);
; #pragma unroll
;                 for (int i = 0; i < 4; ++i) { wsum += t[i]; incl += (4 * j4 + i <= lane) ? t[i] : 0.f; } }
; __device__ __forceinline__ void attn_phase(const Args& a, int l, LAS unsigned char* lds, const int tid, const int rep) {
;     const int lane = tid & 63;
;     unsigned char* ws = a.ws;
;     const bf16_t* U = (const bf16_t*)(ws + WS_U); bf16_t* MIX = (bf16_t*)(ws + WS_MIX); const float* logf = (const float*)(ws + WS_LOGF);
;     unsigned* ctr = (unsigned*)(ws + WS_CTR) + l + 2 * rep;
;     int lop = l; asm volatile("" : "+s"(lop));
;     const float lam_init = 0.8f - 0.6f * expf(-0.3f * (float)lop);
;     float lam;
;     {
;         const float* lv = a.in[10] + l * 256;
;         const float sa = wave_sum(lv[lane] * lv[64 + lane]), sb = wave_sum(lv[128 + lane] * lv[192 + lane]);
;         lam = expf(sa) - expf(sb) + lam_init;
;     }
;     const float* gn = a.in[11] + l * 128;
.LBB0_172:
	s_and_b64 vcc, exec, s[0:1]
	s_cbranch_vccz .LBB0_234
	s_cmp_gt_i32 s5, 0
	s_mov_b64 s[0:1], -1
	s_cbranch_scc0 .LBB0_236
	v_and_b32_e32 v123, 63, v188
	v_readlane_b32 s2, v252, 18
	v_readlane_b32 s0, v252, 29
	v_lshlrev_b32_e32 v0, 2, v123
	v_readlane_b32 s3, v252, 19
	s_nop 4
	global_load_dword v4, v0, s[2:3]
	global_load_dword v5, v0, s[2:3] offset:256
	global_load_dword v6, v0, s[2:3] offset:512
	global_load_dword v7, v0, s[2:3] offset:768
	v_readlane_b32 s1, v252, 30
	v_cmp_gt_u32_e64 s[6:7], 7, v123
	v_readlane_b32 s1, v253, 33
	s_lshl_b32 s20, s1, 1
	v_writelane_b32 v253, s6, 36
	s_lshl_b64 s[2:3], s[20:21], 2
	v_readlane_b32 s1, v252, 8
	v_writelane_b32 v253, s7, 37
	v_cmp_gt_u32_e64 s[6:7], 8, v123
	s_add_u32 s52, s1, s2
	s_mov_b32 s1, 0xc2ce8ed0
	v_writelane_b32 v253, s6, 38
	v_add_u32_e32 v131, 0, v0
	v_mov_b32_e32 v0, 0x3f4ccccd
	v_writelane_b32 v253, s7, 39
	v_cmp_gt_u32_e64 s[6:7], 9, v123
	s_waitcnt vmcnt(0)
	v_bfe_u32 v2, v188, 5, 1
	v_lshlrev_b32_e32 v130, 2, v2
	v_writelane_b32 v253, s6, 40
	v_lshlrev_b32_e32 v8, 3, v188
	v_and_b32_e32 v128, 24, v8
	v_writelane_b32 v253, s7, 41
	v_cmp_gt_u32_e64 s[6:7], 10, v123
	v_and_b32_e32 v122, 31, v188
	v_lshlrev_b32_e32 v124, 2, v188
	v_writelane_b32 v253, s6, 42
	s_waitcnt lgkmcnt(0)
	v_mul_lo_u32 v3, v188, 12
	v_add_u32_e32 v129, 0, v124
	v_writelane_b32 v253, s7, 43
	v_cmp_gt_u32_e64 s[6:7], 11, v123
	v_lshlrev_b32_e32 v126, 3, v2
	v_readlane_b32 s44, v249, 61
	v_writelane_b32 v253, s6, 44
	v_cmp_eq_u32_e64 s[4:5], 0, v188
	v_bfe_u32 v127, v188, 2, 4
	v_writelane_b32 v253, s7, 45
	v_cmp_gt_u32_e64 s[6:7], 12, v123
	v_ashrrev_i32_e32 v125, 31, v124
	v_cmp_eq_u32_e64 s[54:55], 0, v123
	v_writelane_b32 v253, s6, 46
	v_cmp_gt_u32_e64 s[56:57], 2, v123
	v_cmp_gt_u32_e64 s[58:59], 3, v123
	v_writelane_b32 v253, s7, 47
	v_cmp_gt_u32_e64 s[6:7], 13, v123
	v_cmp_gt_u32_e64 s[70:71], 4, v123
	v_cmp_gt_u32_e64 s[72:73], 5, v123
	v_writelane_b32 v253, s6, 48
	v_cmp_gt_u32_e64 s[74:75], 6, v123
	v_not_b32_e32 v145, v188
	v_writelane_b32 v253, s7, 49
	v_cmp_gt_u32_e64 s[6:7], 14, v123
	v_add_u32_e32 v189, 0x200, v188
	v_add_u32_e32 v146, v129, v3
	v_writelane_b32 v253, s6, 50
	v_cmp_gt_u32_e64 s[8:9], 59, v123
	v_cmp_gt_u32_e64 s[10:11], 60, v123
	v_writelane_b32 v253, s7, 51
	v_cmp_gt_u32_e64 s[6:7], 15, v123
	v_cmp_eq_u32_e64 s[38:39], 63, v123
	v_readlane_b32 s45, v249, 62
	v_writelane_b32 v253, s6, 52
	s_movk_i32 s46, 0x3ff
	v_readlane_b32 s47, v251, 14
	v_writelane_b32 v253, s7, 53
	v_cmp_gt_u32_e64 s[6:7], 16, v123
	v_readlane_b32 s48, v251, 15
	v_readlane_b32 s49, v251, 33
	v_writelane_b32 v253, s6, 54
	s_mov_b64 s[50:51], 0x800
	v_mul_f32_e32 v9, v4, v5
	ds_bpermute_b32 v9, v219, v9
	v_mul_f32_e32 v10, v6, v7
	ds_bpermute_b32 v10, v219, v10
	v_writelane_b32 v253, s7, 55
	v_cmp_gt_u32_e64 s[6:7], 17, v123
	s_waitcnt lgkmcnt(1)
	v_fmac_f32_e32 v9, v4, v5
	ds_bpermute_b32 v4, v220, v9
	s_waitcnt lgkmcnt(1)
	v_fmac_f32_e32 v10, v6, v7
	ds_bpermute_b32 v5, v220, v10
	v_writelane_b32 v253, s6, 56
	v_cvt_f32_i32_e32 v6, s0
	s_waitcnt lgkmcnt(1)
	v_add_f32_e32 v4, v9, v4
	v_writelane_b32 v253, s7, 57
	v_cmp_gt_u32_e64 s[6:7], 18, v123
	s_waitcnt lgkmcnt(0)
	v_add_f32_e32 v5, v10, v5
	ds_bpermute_b32 v7, v221, v4
	v_writelane_b32 v253, s6, 58
	ds_bpermute_b32 v9, v221, v5
	v_readlane_b32 s0, v252, 9
	v_writelane_b32 v253, s7, 59
	v_cmp_gt_u32_e64 s[6:7], 19, v123
	s_waitcnt lgkmcnt(1)
	v_add_f32_e32 v4, v4, v7
	s_waitcnt lgkmcnt(0)
	v_add_f32_e32 v5, v5, v9
	v_writelane_b32 v253, s6, 60
	ds_bpermute_b32 v7, v222, v4
	ds_bpermute_b32 v9, v222, v5
	v_writelane_b32 v253, s7, 61
	v_cmp_gt_u32_e64 s[6:7], 20, v123
	v_mul_f32_e32 v6, 0xbe99999a, v6
	s_waitcnt lgkmcnt(1)
	v_add_f32_e32 v4, v4, v7
	v_writelane_b32 v253, s6, 62
	s_waitcnt lgkmcnt(0)
	v_add_f32_e32 v5, v5, v9
	ds_bpermute_b32 v7, v223, v4
	v_writelane_b32 v253, s7, 63
	v_cmp_gt_u32_e64 s[6:7], 21, v123
	ds_bpermute_b32 v9, v223, v5
	s_addc_u32 s53, s0, s3
	v_writelane_b32 v254, s6, 0
	v_mul_f32_e32 v10, 0x3fb8aa3b, v6
	s_mov_b32 s0, 0x3fb8aa3b
	v_writelane_b32 v254, s7, 1
	v_cmp_gt_u32_e64 s[6:7], 22, v123
	s_waitcnt lgkmcnt(1)
	v_add_f32_e32 v4, v4, v7
	v_fma_f32 v11, v6, s0, -v10
	v_writelane_b32 v254, s6, 2
	v_rndne_f32_e32 v12, v10
	s_waitcnt lgkmcnt(0)
	v_add_f32_e32 v5, v5, v9
	v_writelane_b32 v254, s7, 3
	v_cmp_gt_u32_e64 s[6:7], 23, v123
	ds_bpermute_b32 v7, v224, v4
	v_fmac_f32_e32 v11, 0x32a5705f, v6
	v_writelane_b32 v254, s6, 4
	v_sub_f32_e32 v10, v10, v12
	ds_bpermute_b32 v9, v224, v5
	v_writelane_b32 v254, s7, 5
	v_cmp_gt_u32_e64 s[6:7], 24, v123
	v_add_f32_e32 v10, v10, v11
	v_cvt_i32_f32_e32 v12, v12
	v_writelane_b32 v254, s6, 6
	v_exp_f32_e32 v10, v10
	s_waitcnt lgkmcnt(1)
	v_add_f32_e32 v4, v4, v7
	v_writelane_b32 v254, s7, 7
	v_cmp_gt_u32_e64 s[6:7], 25, v123
	s_waitcnt lgkmcnt(0)
; #define LAS __attribute__((address_space(3)))
; template <int DV, int NMAP>
; __device__ __forceinline__ void attn_unit(LAS unsigned char* lds, const bf16_t* U, bf16_t* MIX, const float* logf, int b, int h, int qb, float lam, float slope2, const float* gn, float outscale, const int tid) {
;     ...
;             float incl = 0.f, wsum = 0.f;
; #pragma unroll
;             for (int j4 = 0; j4 < 16; ++j4) { const f32x4 t = *(const LAS f32x4*)(tots + wid * 64 + 4 * j4);
; #pragma unroll
;                 for (int i = 0; i < 4; ++i) { wsum += t[i]; incl += (4 * j4 + i <= lane) ? t[i] : 0.f; } }
; __device__ __forceinline__ void attn_phase(const Args& a, int l, LAS unsigned char* lds, const int tid, const int rep) {
;     ...
;     const float lam_init = 0.8f - 0.6f * expf(-0.3f * (float)lop);
;     float lam;
;     {
;         const float* lv = a.in[10] + l * 256;
;         const float sa = wave_sum(lv[lane] * lv[64 + lane]), sb = wave_sum(lv[128 + lane] * lv[192 + lane]);
;         lam = expf(sa) - expf(sb) + lam_init;
;     }
;     const float* gn = a.in[11] + l * 128;
	v_add_f32_e32 v5, v5, v9
	v_mul_f32_e32 v7, 0x3fb8aa3b, v4
	v_writelane_b32 v254, s6, 8
	v_ldexp_f32 v10, v10, v12
	v_mul_f32_e32 v9, 0x3fb8aa3b, v5
	v_writelane_b32 v254, s7, 9
	v_cmp_gt_u32_e64 s[6:7], 26, v123
	v_fma_f32 v11, v4, s0, -v7
	v_rndne_f32_e32 v12, v7
	v_writelane_b32 v254, s6, 10
	v_fma_f32 v13, v5, s0, -v9
	v_rndne_f32_e32 v14, v9
	v_writelane_b32 v254, s7, 11
	v_cmp_gt_u32_e64 s[6:7], 27, v123
	v_fmac_f32_e32 v11, 0x32a5705f, v4
	v_sub_f32_e32 v7, v7, v12
	v_writelane_b32 v254, s6, 12
	v_fmac_f32_e32 v13, 0x32a5705f, v5
	v_sub_f32_e32 v9, v9, v14
	v_writelane_b32 v254, s7, 13
	v_cmp_gt_u32_e64 s[6:7], 28, v123
	v_add_f32_e32 v7, v7, v11
	v_cvt_i32_f32_e32 v12, v12
	v_writelane_b32 v254, s6, 14
	v_add_f32_e32 v9, v9, v13
	v_exp_f32_e32 v7, v7
	v_writelane_b32 v254, s7, 15
	v_cmp_gt_u32_e64 s[6:7], 29, v123
	v_cvt_i32_f32_e32 v14, v14
	v_exp_f32_e32 v9, v9
	v_writelane_b32 v254, s6, 16
	v_cmp_ngt_f32_e32 vcc, s1, v6
	s_mov_b32 s0, 0x42b17218
	v_writelane_b32 v254, s7, 17
	v_cmp_gt_u32_e64 s[6:7], 30, v123
	v_cndmask_b32_e32 v10, 0, v10, vcc
	v_cmp_nlt_f32_e32 vcc, s0, v6
	v_writelane_b32 v254, s6, 18
	v_ldexp_f32 v7, v7, v12
	v_cndmask_b32_e32 v6, v229, v10, vcc
	v_writelane_b32 v254, s7, 19
	v_cmp_gt_u32_e64 s[6:7], 31, v123
	v_cmp_ngt_f32_e32 vcc, s1, v4
	v_ldexp_f32 v9, v9, v14
	v_writelane_b32 v254, s6, 20
	v_cndmask_b32_e32 v7, 0, v7, vcc
	v_cmp_ngt_f32_e32 vcc, s1, v5
	v_writelane_b32 v254, s7, 21
	v_cmp_gt_u32_e64 s[6:7], 32, v123
	v_cndmask_b32_e32 v9, 0, v9, vcc
	v_cmp_nlt_f32_e32 vcc, s0, v4
	v_writelane_b32 v254, s6, 22
	v_fmamk_f32 v6, v6, 0xbf19999a, v0
	v_cndmask_b32_e32 v4, v229, v7, vcc
	v_writelane_b32 v254, s7, 23
	v_cmp_gt_u32_e64 s[6:7], 33, v123
	v_cmp_nlt_f32_e32 vcc, s0, v5
	v_cmp_gt_u32_e64 s[0:1], 37, v123
	v_writelane_b32 v254, s6, 24
	v_cndmask_b32_e32 v5, v229, v9, vcc
	v_sub_f32_e32 v0, v4, v5
	v_writelane_b32 v254, s7, 25
	v_cmp_gt_u32_e64 s[6:7], 34, v123
	v_add_f32_e32 v140, v6, v0
	v_lshrrev_b32_e32 v0, 2, v188
	v_writelane_b32 v254, s6, 26
	v_and_or_b32 v0, v0, 3, v130
	v_lshlrev_b32_e32 v4, 1, v188
	v_writelane_b32 v254, s7, 27
	v_cmp_gt_u32_e64 s[6:7], 35, v123
	v_and_b32_e32 v4, 32, v4
	v_lshl_add_u32 v0, v0, 6, 0
	v_writelane_b32 v254, s6, 28
	v_add3_u32 v141, v0, v4, v128
	v_lshlrev_b32_e32 v0, 4, v2
	v_writelane_b32 v254, s7, 29
	v_cmp_gt_u32_e64 s[6:7], 36, v123
	v_add_u32_e32 v142, 0, v0
	v_lshlrev_b32_e32 v4, 4, v122
	v_writelane_b32 v254, s6, 30
	v_mul_u32_u24_e32 v2, 0x420, v2
	v_add3_u32 v143, 0, v4, v2
	v_writelane_b32 v254, s7, 31
	v_writelane_b32 v254, s0, 32
	v_sub_f32_e32 v144, 1.0, v6
	v_cmp_gt_u32_e64 s[6:7], 58, v123
	v_writelane_b32 v254, s1, 33
	v_readlane_b32 s0, v252, 22
	v_readlane_b32 s1, v252, 23
	v_cmp_gt_u32_e64 s[2:3], 62, v123
	s_nop 0
	v_lshl_add_u64 v[132:133], s[0:1], 0, v[0:1]
	v_and_b32_e32 v0, 3, v188
	v_readlane_b32 s0, v251, 16
	v_lshlrev_b32_e32 v0, 4, v0
	v_readlane_b32 s1, v251, 17
	s_nop 1
	v_lshl_add_u64 v[134:135], s[0:1], 0, v[0:1]
	v_cmp_gt_u32_e64 s[0:1], 38, v123
	s_nop 1
	v_writelane_b32 v254, s0, 34
	s_nop 1
	v_writelane_b32 v254, s1, 35
	v_cmp_gt_u32_e64 s[0:1], 39, v123
	s_nop 1
	v_writelane_b32 v254, s0, 36
	s_nop 1
	v_writelane_b32 v254, s1, 37
	v_cmp_gt_u32_e64 s[0:1], 40, v123
	s_nop 1
	v_writelane_b32 v254, s0, 38
	s_nop 1
	v_writelane_b32 v254, s1, 39
	v_cmp_gt_u32_e64 s[0:1], 41, v123
	s_nop 1
	v_writelane_b32 v254, s0, 40
	s_nop 1
	v_writelane_b32 v254, s1, 41
	v_cmp_gt_u32_e64 s[0:1], 42, v123
	s_nop 1
	v_writelane_b32 v254, s0, 42
	s_nop 1
	v_writelane_b32 v254, s1, 43
	v_cmp_gt_u32_e64 s[0:1], 43, v123
	s_nop 1
	v_writelane_b32 v254, s0, 44
	s_nop 1
	v_writelane_b32 v254, s1, 45
	v_cmp_gt_u32_e64 s[0:1], 44, v123
	s_nop 1
	v_writelane_b32 v254, s0, 46
	s_nop 1
	v_writelane_b32 v254, s1, 47
	v_cmp_gt_u32_e64 s[0:1], 45, v123
	s_nop 1
	v_writelane_b32 v254, s0, 48
	s_nop 1
	v_writelane_b32 v254, s1, 49
	v_cmp_gt_u32_e64 s[0:1], 46, v123
	s_nop 1
	v_writelane_b32 v254, s0, 50
	s_nop 1
	v_writelane_b32 v254, s1, 51
	v_cmp_gt_u32_e64 s[0:1], 47, v123
	s_nop 1
	v_writelane_b32 v254, s0, 52
	s_nop 1
	v_writelane_b32 v254, s1, 53
	v_cmp_gt_u32_e64 s[0:1], 48, v123
	s_nop 1
	v_writelane_b32 v254, s0, 54
	s_nop 1
	v_writelane_b32 v254, s1, 55
	v_cmp_gt_u32_e64 s[0:1], 49, v123
	s_nop 1
	v_writelane_b32 v254, s0, 56
	s_nop 1
	v_writelane_b32 v254, s1, 57
	v_cmp_gt_u32_e64 s[0:1], 50, v123
	s_nop 1
	v_writelane_b32 v254, s0, 58
	s_nop 1
	v_writelane_b32 v254, s1, 59
	v_cmp_gt_u32_e64 s[0:1], 51, v123
	s_nop 1
	v_writelane_b32 v254, s0, 60
	s_nop 1
	v_writelane_b32 v254, s1, 61
	v_cmp_gt_u32_e64 s[0:1], 52, v123
	s_nop 1
	v_writelane_b32 v254, s0, 62
	s_nop 1
	v_writelane_b32 v254, s1, 63
	v_cmp_gt_u32_e64 s[0:1], 53, v123
	s_nop 1
	v_writelane_b32 v255, s0, 0
	s_nop 1
	v_writelane_b32 v255, s1, 1
	v_cmp_gt_u32_e64 s[0:1], 54, v123
	s_nop 1
	v_writelane_b32 v255, s0, 2
	s_nop 1
	v_writelane_b32 v255, s1, 3
	v_cmp_gt_u32_e64 s[0:1], 55, v123
	s_nop 1
	v_writelane_b32 v255, s0, 4
	s_nop 1
	v_writelane_b32 v255, s1, 5
	v_cmp_gt_u32_e64 s[0:1], 56, v123
	s_nop 1
	v_writelane_b32 v255, s0, 6
	s_nop 1
	v_writelane_b32 v255, s1, 7
	v_cmp_gt_u32_e64 s[0:1], 57, v123
	s_nop 1
	v_writelane_b32 v255, s0, 8
	s_nop 1
	v_writelane_b32 v255, s1, 9
	v_cmp_gt_u32_e64 s[0:1], 61, v123
	v_writelane_b32 v255, s21, 20
	s_branch .LBB0_178

; __device__ __forceinline__ void attn_phase(const Args& a, int l, LAS unsigned char* lds, const int tid, const int rep) {
;     ...
;     for (;;) {
;         if (tid == 0) *nextu = atomicAdd(ctr, 1u);
;         __syncthreads();
;         const unsigned i = *nextu;
;         __syncthreads();
;         if (i >= 1024u) break;
;         if (i < 512u) {
;             const int qb = 15 - (int)(i >> 5), bh = (int)(i & 31), b = bh >> 2, h = bh & 3;
.LBB0_178:
	v_readlane_b32 s20, v251, 11
	s_cmp_lg_u32 s20, 0x4000
	s_cbranch_scc1 .Lat_dyn
	v_readlane_b32 s20, v255, 20
	v_readlane_b32 s36, v249, 0
	s_add_i32 s27, s20, 1
	s_nop 1
	v_writelane_b32 v255, s27, 20
	s_cmp_eq_u32 s20, 1
	s_cselect_b32 s27, 0x1e0, 0
	s_cmp_eq_u32 s20, 2
	s_cselect_b32 s27, 0x200, s27
	s_cmp_eq_u32 s20, 3
	s_cselect_b32 s27, 0x3c0, s27
	s_xor_b32 s27, s27, s36
	s_cmp_gt_u32 s20, 3
	s_cselect_b32 s27, 0x400, s27
	v_mov_b32_e32 v0, s27
	s_mov_b64 s[30:31], -1
	s_branch .Lat_disp

; template <int DV, int NMAP>
; __device__ __forceinline__ void attn_unit(LAS unsigned char* lds, const bf16_t* U, bf16_t* MIX, const float* logf, int b, int h, int qb, float lam, float slope2, const float* gn, float outscale, const int tid) {
;     ...
;             if (4 * tid < n) { const float* lp = logf + (rowbase + 4 * tid) * 8 + h; v0 = lp[0]; v1 = lp[8]; v2 = lp[16]; v3 = lp[24]; }
; __device__ __forceinline__ void attn_phase(const Args& a, int l, LAS unsigned char* lds, const int tid, const int rep) {
;     ...
;         const unsigned i = *nextu;
;         __syncthreads();
;         if (i >= 1024u) break;
;         if (i < 512u) {
;             const int qb = 15 - (int)(i >> 5), bh = (int)(i & 31), b = bh >> 2, h = bh & 3;
;             const float slope2 = exp2f(-2.0f * (float)(h + 1)) * LOG2E;
;             attn_unit<128, 2>(lds, U, MIX, logf, b, h, qb, lam, slope2, gn, 1.0f - lam_init, tid);
;         } else {
;             const int j = (int)i - 512, qb = 7 - (j >> 6), bh = j & 63, b = bh >> 3, h = bh & 7;
;             attn_unit<64, 1>(lds, U, MIX, logf, b, h, qb, 0.f, 0.f, gn, 1.f, tid);
.Lat_disp:
	v_cmp_lt_u32_e32 vcc, s46, v0
	v_readfirstlane_b32 s27, v0
	s_cbranch_vccnz .LBB0_177
	s_cmpk_gt_u32 s27, 0x1ff
	s_cbranch_scc0 .LBB0_206
	s_not_b32 s20, s27
	s_lshl_b32 s20, s20, 2
	s_and_b32 s33, s20, 0xf00
	s_lshl_b32 s20, s27, 8
	s_add_i32 s37, s33, 0x100
	s_and_b32 s60, s27, 7
	v_readfirstlane_b32 s41, v188
	s_and_b32 s20, s20, 0x3800
	v_cmp_gt_i32_e32 vcc, s37, v124
	v_mov_b32_e32 v0, 0
	v_mov_b32_e32 v2, 0
	v_mov_b32_e32 v3, 0
	v_mov_b32_e32 v66, 0
	s_and_saveexec_b64 s[30:31], vcc
	s_cbranch_execz .LBB0_186
	v_lshl_add_u64 v[2:3], s[20:21], 0, v[124:125]
	v_lshlrev_b64 v[2:3], 5, v[2:3]
	v_lshl_add_u64 v[2:3], s[44:45], 0, v[2:3]
	s_lshl_b32 s62, s60, 2
	s_mov_b32 s63, s21
	v_lshl_add_u64 v[4:5], v[2:3], 0, s[62:63]
	global_load_dword v66, v[4:5], off
	global_load_dword v3, v[4:5], off offset:32
	global_load_dword v2, v[4:5], off offset:64
	global_load_dword v0, v[4:5], off offset:96

; template <int DV, int NMAP>
; __device__ __forceinline__ void attn_unit(LAS unsigned char* lds, const bf16_t* U, bf16_t* MIX, const float* logf, int b, int h, int qb, float lam, float slope2, const float* gn, float outscale, const int tid) {
;     ...
;     bf16x8 qr[4];
;     {
;         const bf16_t* qp = U + (rowbase + qrow0 + r32) * UW + qcol + map * 64 + hi * 8;
; #pragma unroll
;         for (int d0 = 0; d0 < 4; ++d0) qr[d0] = *(const bf16x8*)(qp + 16 * d0);
;     }
;     asm volatile("" : "+v"(qr[0]), "+v"(qr[1]), "+v"(qr[2]), "+v"(qr[3]));
;     const bf16_t* kg = U + (rowbase + lane) * UW + kcol + wid * 8;
;     const bf16_t* vg = U + (rowbase + 16 * (wid & 3) + (lane >> 2)) * UW + vcol + (wid >> 2) * 32 + (lane & 3) * 8;
;     const unsigned ldsb = (unsigned)(size_t)lds;
;     ...
;     __syncthreads();
;     AT_DMA(0, 0);
;     if (NT > 1) AT_DMA(1, 1);
;     const float m_run = bias[qrow0 + r32];
;     float l_run = 0.f;
;     f32x16 o[NDB];
; #pragma unroll
;     for (int d = 0; d < NDB; ++d)
; #pragma unroll
;         for (int r = 0; r < 16; ++r) o[d][r] = 0.f;
;     const int vofs = (4 * hi + ((lane & 15) >> 2)) * 64 + ((lane >> 4) & 1) * 32 + (lane & 3) * 8;
;     int st = 0, st2 = 2;
.LBB0_193:
	s_or_b64 exec, exec, s[30:31]
	s_lshl_b32 s36, s40, 5
	s_add_i32 s36, s36, s33
	s_lshr_b32 s37, s37, 6
	s_lshl_b32 s33, s60, 6
	s_ashr_i32 s30, s36, 31
	s_add_u32 s31, s36, s20
	v_or_b32_e32 v98, s31, v122
	v_mov_b64_e32 v[2:3], s[84:85]
	s_addc_u32 s61, s30, 0
	v_mad_u64_u32 v[2:3], s[30:31], v98, s87, v[2:3]
	v_mov_b32_e32 v0, 0x1800
	v_mad_i32_i24 v3, s61, v0, v3
	s_lshl_b32 s30, s60, 7
	s_mov_b32 s31, s21
	v_lshl_add_u64 v[2:3], v[2:3], 0, s[30:31]
	v_lshlrev_b32_e32 v0, 1, v126
	v_lshl_add_u64 v[2:3], v[2:3], 0, v[0:1]
	global_load_dwordx4 v[66:69], v[2:3], off offset:96
	global_load_dwordx4 v[70:73], v[2:3], off offset:64
	global_load_dwordx4 v[74:77], v[2:3], off offset:32
	global_load_dwordx4 v[78:81], v[2:3], off
	v_or_b32_e32 v0, s20, v123
	v_mul_u32_u24_e32 v0, 0xc00, v0
	v_lshlrev_b32_e32 v0, 1, v0
	v_lshl_add_u64 v[2:3], s[84:85], 0, v[0:1]
	s_lshl_b32 s60, s40, 3
	v_mov_b32_e32 v99, s61
	v_lshl_add_u64 v[2:3], v[2:3], 0, s[30:31]
	s_ashr_i32 s61, s60, 31
	v_lshl_add_u64 v[2:3], s[60:61], 1, v[2:3]
	s_mov_b64 s[60:61], 0x400
	v_lshl_add_u64 v[4:5], v[2:3], 0, s[60:61]
	s_bfe_u32 s60, s41, 0x20006
	v_lshl_or_b32 v0, s60, 4, v127
	v_or_b32_e32 v0, s20, v0
	v_mul_u32_u24_e32 v0, 0xc00, v0
	v_lshlrev_b32_e32 v0, 1, v0
	v_lshl_add_u64 v[6:7], s[84:85], 0, v[0:1]
	s_ashr_i32 s41, s41, 8
	v_lshl_add_u64 v[6:7], v[6:7], 0, s[30:31]
	s_lshl_b32 s30, s41, 5
	s_ashr_i32 s31, s30, 31
	s_mul_i32 s61, s40, 0x420
	v_lshl_add_u64 v[6:7], s[30:31], 1, v[6:7]
	s_add_i32 s20, s61, s49
	s_lshl_b32 s31, s60, 10
	v_lshlrev_b32_e32 v0, 1, v128
	v_lshl_add_u64 v[6:7], v[6:7], 0, v[0:1]
	v_lshl_add_u64 v[8:9], v[6:7], 0, s[50:51]
	v_or_b32_e32 v0, s36, v122
	v_mov_b32_e32 v105, 0
	s_or_b32 s60, s36, 31
	s_mov_b32 s64, 0
	v_mov_b32_e32 v106, v142
	s_mov_b32 s62, 0
	v_mov_b32_e32 v10, v105
	v_mov_b32_e32 v11, v105
	v_mov_b32_e32 v12, v105
	v_mov_b32_e32 v13, v105
	v_mov_b32_e32 v14, v105
	v_mov_b32_e32 v15, v105
	v_mov_b32_e32 v16, v105
	v_mov_b32_e32 v17, v105
	v_mov_b32_e32 v18, 0
	v_mov_b32_e32 v19, v105
	v_mov_b32_e32 v20, v105
	v_mov_b32_e32 v21, v105
	v_mov_b32_e32 v22, v105
	v_mov_b32_e32 v23, v105
	v_mov_b32_e32 v24, v105
	v_mov_b32_e32 v25, v105
	v_mov_b32_e32 v26, v105
	v_mov_b32_e32 v27, v105
	v_mov_b32_e32 v28, v105
	v_mov_b32_e32 v29, v105
	v_mov_b32_e32 v30, v105
	v_mov_b32_e32 v31, v105
	v_mov_b32_e32 v32, v105
	v_mov_b32_e32 v33, v105
	s_waitcnt vmcnt(0)
	s_waitcnt lgkmcnt(0)
	s_barrier
	s_mov_b32 s67, m0
	s_mov_b32 s65, s41
	s_mov_b32 s68, s40
	s_lshr_b32 s66, s60, 6
	s_mov_b32 s64, 0
	v_and_b32_e32 v180, 7, v123
	v_sub_u32_e32 v180, v180, v123
	s_lshl_b32 s30, s68, 3
	v_add_u32_e32 v180, s30, v180
	v_mul_i32_i24_e32 v180, 0x1800, v180
	v_lshrrev_b32_e32 v181, 3, v123
	v_subrev_u32_e32 v181, s68, v181
	v_lshl_add_u32 v180, v181, 4, v180
	v_ashrrev_i32_e32 v181, 31, v180
	v_lshl_add_u64 v[102:103], v[2:3], 0, v[180:181]
	v_bfe_u32 v180, v123, 2, 3
	v_lshrrev_b32_e32 v181, 2, v123
	v_sub_u32_e32 v180, v180, v181
	s_and_b32 s31, s68, 3
	s_lshl_b32 s31, s31, 4
	s_lshl_b32 s30, s68, 3
	s_sub_i32 s30, s30, s31
	v_add_u32_e32 v180, s30, v180
	v_mul_i32_i24_e32 v180, 0x1800, v180
	v_lshrrev_b32_e32 v181, 5, v123
	s_lshr_b32 s31, s68, 2
	v_subrev_u32_e32 v181, s31, v181
	v_lshl_add_u32 v180, v181, 6, v180
	v_ashrrev_i32_e32 v181, 31, v180
	v_lshl_add_u64 v[100:101], v[6:7], 0, v[180:181]
	s_lshr_b32 s30, s68, 2
	s_mul_i32 s30, s30, 0x1080
	s_and_b32 s31, s68, 3
	s_lshl_b32 s31, s31, 10
	s_add_i32 s30, s30, s31
	s_bfe_u32 s31, s68, 0x10001
	s_lshl_b32 s31, s31, 7
	s_add_i32 s30, s30, s31
	s_add_i32 s20, s30, 0x2100
	s_mul_i32 s30, s68, 0x400
	s_add_i32 s40, s30, 0xa500
	v_lshrrev_b32_e32 v180, 3, v122
	v_lshlrev_b32_e32 v180, 10, v180
	v_bfe_u32 v181, v122, 4, 1
	v_lshl_add_u32 v180, v181, 7, v180
	v_lshrrev_b32_e32 v181, 5, v123
	v_lshl_add_u32 v180, v181, 7, v180
	v_and_b32_e32 v181, 7, v122
	v_lshl_add_u32 v244, v181, 4, v180
	s_mov_b64 s[30:31], 0x400
	v_lshl_add_u64 v[102:103], v[102:103], 0, s[30:31]
	s_mov_b64 s[30:31], 0x800
	v_lshl_add_u64 v[100:101], v[100:101], 0, s[30:31]
	v_lshl_add_u32 v121, v0, 2, 0
	s_mov_b32 m0, s20
	s_nop 0
	global_load_lds_dwordx4 v[102:103], off
	s_mov_b32 m0, s40
	s_nop 0
	global_load_lds_dwordx4 v[100:101], off
	v_lshl_add_u64 v[102:103], v[102:103], 0, s[28:29]
	v_lshl_add_u64 v[100:101], v[100:101], 0, s[28:29]
	s_add_i32 s30, s20, 0x2100
	s_mov_b32 m0, s30
	s_nop 0
	global_load_lds_dwordx4 v[102:103], off
	s_add_i32 s30, s40, 0x2000
	s_mov_b32 m0, s30
	s_nop 0
	global_load_lds_dwordx4 v[100:101], off
	v_lshl_add_u64 v[102:103], v[102:103], 0, s[28:29]
	v_lshl_add_u64 v[100:101], v[100:101], 0, s[28:29]
	s_add_i32 s30, s20, 0x4200
	s_mov_b32 m0, s30
	s_nop 0
	global_load_lds_dwordx4 v[102:103], off
	s_add_i32 s30, s40, 0x4000
	s_mov_b32 m0, s30
	s_nop 0
	global_load_lds_dwordx4 v[100:101], off
	v_lshl_add_u64 v[102:103], v[102:103], 0, s[28:29]
	v_lshl_add_u64 v[100:101], v[100:101], 0, s[28:29]
	ds_read_b32 v104, v121
	v_mov_b32_e32 v2, 0
	v_mov_b32_e32 v3, 0
	v_mov_b32_e32 v4, 0
	v_mov_b32_e32 v5, 0
	v_mov_b32_e32 v6, 0
	v_mov_b32_e32 v7, 0
	v_mov_b32_e32 v8, 0
	v_mov_b32_e32 v9, 0
	s_waitcnt vmcnt(4)
	s_barrier
	s_cmp_eq_u32 s65, 0
	s_cbranch_scc1 .Lfx_P
	s_barrier
; #define LAS __attribute__((address_space(3)))
; template <int DV, int NMAP>
; __device__ __forceinline__ void attn_unit(LAS unsigned char* lds, const bf16_t* U, bf16_t* MIX, const float* logf, int b, int h, int qb, float lam, float slope2, const float* gn, float outscale, const int tid) {
;     ...
;         if (64 * t <= qrow0 + 31) {
;             const LAS unsigned char* Kb = lds + AT_K + (st * NMAP + map) * AT_KT + r32 * 16;
;             const LAS unsigned char* Vb = lds + AT_V + st * VT + vofs;
;             f32x16 p0, p1;
;             {
;                 const LAS float* bp = bias + 64 * t + 4 * hi;
; #pragma unroll
;                 for (int g = 0; g < 4; ++g) { const f32x4 v = *(const LAS f32x4*)(bp + 8 * g), w = *(const LAS f32x4*)(bp + 32 + 8 * g);
;                     p0[4 * g] = v[0]; p0[4 * g + 1] = v[1]; p0[4 * g + 2] = v[2]; p0[4 * g + 3] = v[3]; p1[4 * g] = w[0]; p1[4 * g + 1] = w[1]; p1[4 * g + 2] = w[2]; p1[4 * g + 3] = w[3]; }
;             }
;             {
;                 bf16x8 kf[8];
; #pragma unroll
;                 for (int d0 = 0; d0 < 4; ++d0) { kf[2 * d0] = *(const LAS bf16x8*)(Kb + (2 * d0 + hi) * 1056); kf[2 * d0 + 1] = *(const LAS bf16x8*)(Kb + (2 * d0 + hi) * 1056 + 512); }
;                 __builtin_amdgcn_sched_barrier(0);
; #pragma unroll
;                 for (int d0 = 0; d0 < 4; ++d0) {
;                     p0 = __builtin_amdgcn_mfma_f32_32x32x16_bf16(kf[2 * d0], qr[d0], p0, 0, 0, 0);
;                     p1 = __builtin_amdgcn_mfma_f32_32x32x16_bf16(kf[2 * d0 + 1], qr[d0], p1, 0, 0, 0);
;                 }
;                 __builtin_amdgcn_sched_barrier(0);
;             }
;             if (64 * t + 63 > qrow0) {
;                 const int q = qrow0 + r32, kv0 = 64 * t + 4 * hi;
; #pragma unroll
;                 for (int r = 0; r < 16; ++r) { const int kv = kv0 + (r & 3) + 8 * (r >> 2); if (kv > q) p0[r] = -1e30f; if (kv + 32 > q) p1[r] = -1e30f; }
;             }
.Lfx_P:
	v_mov_b32_e32 v107, v244
	ds_read_b128 v[50:53], v106
	ds_read_b128 v[54:57], v106 offset:32
	ds_read_b128 v[58:61], v106 offset:64
	ds_read_b128 v[62:65], v106 offset:96
	ds_read_b128 v[34:37], v106 offset:128
	ds_read_b128 v[38:41], v106 offset:160
	ds_read_b128 v[42:45], v106 offset:192
	ds_read_b128 v[46:49], v106 offset:224
	ds_read_b128 v[82:85], v107 offset:8448
	ds_read_b128 v[86:89], v107 offset:12672
	ds_read_b128 v[90:93], v107 offset:8704
	ds_read_b128 v[94:97], v107 offset:12928
	ds_read_b128 v[108:111], v107 offset:8960
	ds_read_b128 v[112:115], v107 offset:13184
	ds_read_b128 v[116:119], v107 offset:9216
	ds_read_b128 v[136:139], v107 offset:13440
	s_waitcnt lgkmcnt(7)
	v_mfma_f32_32x32x16_bf16 v[50:65], v[82:85], v[78:81], v[50:65]
	s_waitcnt lgkmcnt(6)
	v_mfma_f32_32x32x16_bf16 v[34:49], v[86:89], v[78:81], v[34:49]
	s_waitcnt lgkmcnt(5)
	v_mfma_f32_32x32x16_bf16 v[50:65], v[90:93], v[74:77], v[50:65]
	s_waitcnt lgkmcnt(4)
	v_mfma_f32_32x32x16_bf16 v[34:49], v[94:97], v[74:77], v[34:49]
	s_waitcnt lgkmcnt(3)
	v_mfma_f32_32x32x16_bf16 v[50:65], v[108:111], v[70:73], v[50:65]
	s_waitcnt lgkmcnt(2)
	v_mfma_f32_32x32x16_bf16 v[34:49], v[112:115], v[70:73], v[34:49]
	s_waitcnt lgkmcnt(1)
	v_mfma_f32_32x32x16_bf16 v[50:65], v[116:119], v[66:69], v[50:65]
	s_waitcnt lgkmcnt(0)
	v_mfma_f32_32x32x16_bf16 v[34:49], v[136:139], v[66:69], v[34:49]
	s_movk_i32 s61, 63
	s_cmp_le_i32 s61, s36
	s_cbranch_scc1 .Lfx_P_nomask
	v_add_u32_e32 v82, s61, v130
	v_subrev_u32_e32 v84, 31, v82
	v_subrev_u32_e32 v83, 63, v82
	v_cmp_le_i32_e32 vcc, v84, v0
	s_nop 5
	v_cndmask_b32_e32 v34, v230, v34, vcc
	v_cmp_lt_i32_e32 vcc, v83, v0
	s_nop 1
	v_cndmask_b32_e32 v51, v230, v51, vcc
	v_cmp_le_i32_e32 vcc, v83, v0
	v_subrev_u32_e32 v83, 30, v82
	s_nop 0
	v_cndmask_b32_e32 v50, v230, v50, vcc
	v_cmp_le_i32_e32 vcc, v83, v0
	v_subrev_u32_e32 v83, 61, v82
	s_nop 0
	v_cndmask_b32_e32 v35, v230, v35, vcc
	v_cmp_le_i32_e32 vcc, v83, v0
	v_subrev_u32_e32 v83, 29, v82
	s_nop 0
	v_cndmask_b32_e32 v52, v230, v52, vcc
	v_cmp_le_i32_e32 vcc, v83, v0
	v_subrev_u32_e32 v83, 60, v82
	s_nop 0
	v_cndmask_b32_e32 v36, v230, v36, vcc
	v_cmp_le_i32_e32 vcc, v83, v0
	v_subrev_u32_e32 v83, 28, v82
	s_nop 0
	v_cndmask_b32_e32 v53, v230, v53, vcc
	v_cmp_le_i32_e32 vcc, v83, v0
	v_subrev_u32_e32 v83, 55, v82
	s_nop 0
	v_cndmask_b32_e32 v37, v230, v37, vcc
	v_cmp_le_i32_e32 vcc, v83, v0
	v_subrev_u32_e32 v83, 23, v82
	s_nop 0
	v_cndmask_b32_e32 v54, v230, v54, vcc
	v_cmp_le_i32_e32 vcc, v83, v0
	v_subrev_u32_e32 v83, 54, v82
	s_nop 0
	v_cndmask_b32_e32 v38, v230, v38, vcc
	v_cmp_le_i32_e32 vcc, v83, v0
	v_subrev_u32_e32 v83, 22, v82
	s_nop 0
	v_cndmask_b32_e32 v55, v230, v55, vcc
	v_cmp_le_i32_e32 vcc, v83, v0
	v_subrev_u32_e32 v83, 53, v82
	s_nop 0
	v_cndmask_b32_e32 v39, v230, v39, vcc
	v_cmp_le_i32_e32 vcc, v83, v0
	v_subrev_u32_e32 v83, 21, v82
	s_nop 0
	v_cndmask_b32_e32 v56, v230, v56, vcc
	v_cmp_le_i32_e32 vcc, v83, v0
	v_subrev_u32_e32 v83, 52, v82
	s_nop 0
	v_cndmask_b32_e32 v40, v230, v40, vcc
	v_cmp_le_i32_e32 vcc, v83, v0
	v_subrev_u32_e32 v83, 20, v82
	s_nop 0
	v_cndmask_b32_e32 v57, v230, v57, vcc
	v_cmp_le_i32_e32 vcc, v83, v0
	v_subrev_u32_e32 v83, 47, v82
	s_nop 0
	v_cndmask_b32_e32 v41, v230, v41, vcc
	v_cmp_le_i32_e32 vcc, v83, v0
	v_add_u32_e32 v83, -15, v82
	s_nop 0
	v_cndmask_b32_e32 v58, v230, v58, vcc
	v_cmp_le_i32_e32 vcc, v83, v0
	v_subrev_u32_e32 v83, 46, v82
	s_nop 0
	v_cndmask_b32_e32 v42, v230, v42, vcc
	v_cmp_le_i32_e32 vcc, v83, v0
	v_add_u32_e32 v83, -14, v82
	s_nop 0
	v_cndmask_b32_e32 v59, v230, v59, vcc
	v_cmp_le_i32_e32 vcc, v83, v0
	v_subrev_u32_e32 v83, 45, v82
	s_nop 0
	v_cndmask_b32_e32 v43, v230, v43, vcc
	v_cmp_le_i32_e32 vcc, v83, v0
	v_add_u32_e32 v83, -13, v82
	s_nop 0
	v_cndmask_b32_e32 v60, v230, v60, vcc
	v_cmp_le_i32_e32 vcc, v83, v0
	v_subrev_u32_e32 v83, 44, v82
	s_nop 0
	v_cndmask_b32_e32 v44, v230, v44, vcc
	v_cmp_le_i32_e32 vcc, v83, v0
	v_add_u32_e32 v83, -12, v82
	s_nop 0
	v_cndmask_b32_e32 v61, v230, v61, vcc
	v_cmp_le_i32_e32 vcc, v83, v0
	v_subrev_u32_e32 v83, 39, v82
	s_nop 0
	v_cndmask_b32_e32 v45, v230, v45, vcc
	v_cmp_le_i32_e32 vcc, v83, v0
	v_add_u32_e32 v83, -7, v82
	s_nop 0
	v_cndmask_b32_e32 v62, v230, v62, vcc
	v_cmp_le_i32_e32 vcc, v83, v0
	v_subrev_u32_e32 v83, 38, v82
	s_nop 0
	v_cndmask_b32_e32 v46, v230, v46, vcc
	v_cmp_le_i32_e32 vcc, v83, v0
	v_add_u32_e32 v83, -6, v82
	s_nop 0
	v_cndmask_b32_e32 v63, v230, v63, vcc
	v_cmp_le_i32_e32 vcc, v83, v0
	v_subrev_u32_e32 v83, 37, v82
	s_nop 0
	v_cndmask_b32_e32 v47, v230, v47, vcc
	v_cmp_le_i32_e32 vcc, v83, v0
	v_add_u32_e32 v83, -5, v82
	s_nop 0
	v_cndmask_b32_e32 v64, v230, v64, vcc
	v_cmp_le_i32_e32 vcc, v83, v0
	v_subrev_u32_e32 v83, 36, v82
	v_add_u32_e32 v82, -4, v82
	v_cndmask_b32_e32 v48, v230, v48, vcc
	v_cmp_le_i32_e32 vcc, v83, v0
	s_nop 1
	v_cndmask_b32_e32 v65, v230, v65, vcc
	v_cmp_le_i32_e32 vcc, v82, v0
	s_nop 1
	v_cndmask_b32_e32 v49, v230, v49, vcc
.Lfx_P_nomask:
	s_cmp_eq_u32 s65, 0
	s_cbranch_scc1 .Lfx_bP_done
	s_waitcnt vmcnt(2)

; __device__ __forceinline__ unsigned pk_bf16(float lo, float hi) { return pg8::cvt_pk_bf16(lo, hi); }
; __device__ __forceinline__ s16x4 vtr(const LAS unsigned char* p) { typedef short v4i16_t __attribute__((ext_vector_type(4))); return __builtin_bit_cast(s16x4, __builtin_amdgcn_ds_read_tr16_b64_v4i16((LAS v4i16_t*)p)); }
; template <int DV, int NMAP>
; __device__ __forceinline__ void attn_unit(LAS unsigned char* lds, const bf16_t* U, bf16_t* MIX, const float* logf, int b, int h, int qb, float lam, float slope2, const float* gn, float outscale, const int tid) {
;     ...
;             s16x4 lo[2][4], hh[2][4];
; #pragma unroll
;             for (int e = 0; e < 2; ++e)
; #pragma unroll
;                 for (int s = 0; s < 4; ++s) { lo[e][s] = vtr(Vb + e * 4096 + s * 1024); hh[e][s] = vtr(Vb + e * 4096 + s * 1024 + 512); }
;             __builtin_amdgcn_sched_barrier(0);
;             {
;                 float s0 = 0.f, s1 = 0.f, s2 = 0.f, s3 = 0.f;
; #pragma unroll
;                 for (int r = 0; r < 16; r += 2) { p0[r] = __builtin_amdgcn_exp2f(p0[r] - m_run); p0[r + 1] = __builtin_amdgcn_exp2f(p0[r + 1] - m_run); p1[r] = __builtin_amdgcn_exp2f(p1[r] - m_run); p1[r + 1] = __builtin_amdgcn_exp2f(p1[r + 1] - m_run);
;                     s0 += p0[r]; s1 += p0[r + 1]; s2 += p1[r]; s3 += p1[r + 1]; }
;                 l_run += (s0 + s1) + (s2 + s3);
;             }
;             bf16x8 pk[4];
;             {
;                 u32x4 w;
;                 w.x = pk_bf16(p0[0], p0[1]); w.y = pk_bf16(p0[2], p0[3]); w.z = pk_bf16(p0[4], p0[5]); w.w = pk_bf16(p0[6], p0[7]); pk[0] = __builtin_bit_cast(bf16x8, w);
;                 w.x = pk_bf16(p0[8], p0[9]); w.y = pk_bf16(p0[10], p0[11]); w.z = pk_bf16(p0[12], p0[13]); w.w = pk_bf16(p0[14], p0[15]); pk[1] = __builtin_bit_cast(bf16x8, w);
;                 w.x = pk_bf16(p1[0], p1[1]); w.y = pk_bf16(p1[2], p1[3]); w.z = pk_bf16(p1[4], p1[5]); w.w = pk_bf16(p1[6], p1[7]); pk[2] = __builtin_bit_cast(bf16x8, w);
;                 w.x = pk_bf16(p1[8], p1[9]); w.y = pk_bf16(p1[10], p1[11]); w.z = pk_bf16(p1[12], p1[13]); w.w = pk_bf16(p1[14], p1[15]); pk[3] = __builtin_bit_cast(bf16x8, w);
;             }
.Lfx_loop:
	s_cmp_gt_u32 s64, s66
	s_cbranch_scc1 .Lfx_A_skip
	s_and_b32 s62, s64, 3
	s_lshl_b32 s30, s62, 13
	v_add_u32_e32 v120, s30, v141
	ds_read_b64_tr_b16 v[148:149], v120 offset:42240
	ds_read_b64_tr_b16 v[150:151], v120 offset:43264
	ds_read_b64_tr_b16 v[152:153], v120 offset:44288
	ds_read_b64_tr_b16 v[154:155], v120 offset:45312
	ds_read_b64_tr_b16 v[156:157], v120 offset:46336
	ds_read_b64_tr_b16 v[158:159], v120 offset:47360
	ds_read_b64_tr_b16 v[160:161], v120 offset:48384
	ds_read_b64_tr_b16 v[162:163], v120 offset:49408
	ds_read_b64_tr_b16 v[164:165], v120 offset:42752
	ds_read_b64_tr_b16 v[166:167], v120 offset:43776
	ds_read_b64_tr_b16 v[168:169], v120 offset:44800
	ds_read_b64_tr_b16 v[170:171], v120 offset:45824
	ds_read_b64_tr_b16 v[172:173], v120 offset:46848
	ds_read_b64_tr_b16 v[174:175], v120 offset:47872
	ds_read_b64_tr_b16 v[176:177], v120 offset:48896
	ds_read_b64_tr_b16 v[178:179], v120 offset:49920
	v_sub_f32_e32 v50, v50, v104
	v_sub_f32_e32 v34, v34, v104
	v_sub_f32_e32 v51, v51, v104
	v_exp_f32_e32 v50, v50
	v_sub_f32_e32 v35, v35, v104
	v_exp_f32_e32 v34, v34
	v_sub_f32_e32 v52, v52, v104
	v_exp_f32_e32 v51, v51
	v_sub_f32_e32 v36, v36, v104
	v_exp_f32_e32 v35, v35
	v_sub_f32_e32 v53, v53, v104
	v_exp_f32_e32 v52, v52
	v_sub_f32_e32 v37, v37, v104
	v_exp_f32_e32 v36, v36
	v_sub_f32_e32 v54, v54, v104
	v_exp_f32_e32 v53, v53
	v_sub_f32_e32 v38, v38, v104
	v_exp_f32_e32 v37, v37
	v_sub_f32_e32 v55, v55, v104
	v_exp_f32_e32 v54, v54
	v_sub_f32_e32 v39, v39, v104
	v_exp_f32_e32 v38, v38
	v_sub_f32_e32 v56, v56, v104
	v_exp_f32_e32 v55, v55
	v_sub_f32_e32 v40, v40, v104
	v_exp_f32_e32 v39, v39
	v_sub_f32_e32 v57, v57, v104
	v_exp_f32_e32 v56, v56
	v_sub_f32_e32 v41, v41, v104
	v_exp_f32_e32 v40, v40
	v_sub_f32_e32 v58, v58, v104
	v_exp_f32_e32 v57, v57
	v_sub_f32_e32 v42, v42, v104
	v_exp_f32_e32 v41, v41
	v_sub_f32_e32 v59, v59, v104
	v_exp_f32_e32 v58, v58
	v_sub_f32_e32 v43, v43, v104
	v_exp_f32_e32 v42, v42
	v_sub_f32_e32 v60, v60, v104
	v_exp_f32_e32 v59, v59
	v_sub_f32_e32 v44, v44, v104
	v_exp_f32_e32 v43, v43
	v_sub_f32_e32 v61, v61, v104
	v_exp_f32_e32 v60, v60
	v_sub_f32_e32 v45, v45, v104
	v_exp_f32_e32 v44, v44
	v_sub_f32_e32 v62, v62, v104
	v_exp_f32_e32 v61, v61
	v_sub_f32_e32 v46, v46, v104
	v_exp_f32_e32 v45, v45
	v_sub_f32_e32 v63, v63, v104
	v_exp_f32_e32 v62, v62
	v_sub_f32_e32 v47, v47, v104
	v_exp_f32_e32 v46, v46
	v_sub_f32_e32 v64, v64, v104
	v_exp_f32_e32 v63, v63
	v_sub_f32_e32 v48, v48, v104
	v_exp_f32_e32 v47, v47
	v_sub_f32_e32 v65, v65, v104
	v_exp_f32_e32 v64, v64
	v_sub_f32_e32 v49, v49, v104
	v_exp_f32_e32 v48, v48
	v_exp_f32_e32 v65, v65
	v_exp_f32_e32 v49, v49
	s_nop 0
	v_add_f32_e32 v180, v50, v51
	v_add_f32_e32 v181, v52, v53
	v_add_f32_e32 v182, v34, v35
	v_add_f32_e32 v121, v36, v37
	v_add_f32_e32 v180, v180, v54
	v_add_f32_e32 v181, v181, v55
	v_add_f32_e32 v182, v182, v38
	v_add_f32_e32 v121, v121, v39
	v_add_f32_e32 v180, v180, v56
	v_add_f32_e32 v181, v181, v57
	v_add_f32_e32 v182, v182, v40
	v_add_f32_e32 v121, v121, v41
	v_add_f32_e32 v180, v180, v58
	v_add_f32_e32 v181, v181, v59
	v_add_f32_e32 v182, v182, v42
	v_add_f32_e32 v121, v121, v43
	v_add_f32_e32 v180, v180, v60
	v_add_f32_e32 v181, v181, v61
	v_add_f32_e32 v182, v182, v44
	v_add_f32_e32 v121, v121, v45
	v_add_f32_e32 v180, v180, v62
	v_add_f32_e32 v181, v181, v63
	v_add_f32_e32 v182, v182, v46
	v_add_f32_e32 v121, v121, v47
	v_add_f32_e32 v180, v180, v64
	v_add_f32_e32 v181, v181, v65
	v_add_f32_e32 v182, v182, v48
	v_add_f32_e32 v121, v121, v49
	v_add_f32_e32 v180, v180, v181
	v_add_f32_e32 v182, v182, v121
	v_cvt_pk_bf16_f32 v202, v50, v51
	v_cvt_pk_bf16_f32 v203, v52, v53
	v_cvt_pk_bf16_f32 v204, v54, v55
	v_cvt_pk_bf16_f32 v205, v56, v57
	v_cvt_pk_bf16_f32 v206, v58, v59
	v_cvt_pk_bf16_f32 v207, v60, v61
	v_cvt_pk_bf16_f32 v208, v62, v63
	v_cvt_pk_bf16_f32 v209, v64, v65
	v_add_f32_e32 v180, v180, v182
	v_cvt_pk_bf16_f32 v210, v34, v35
	v_cvt_pk_bf16_f32 v211, v36, v37
	v_cvt_pk_bf16_f32 v212, v38, v39
	v_cvt_pk_bf16_f32 v213, v40, v41
	v_cvt_pk_bf16_f32 v214, v42, v43
	v_cvt_pk_bf16_f32 v215, v44, v45
	v_cvt_pk_bf16_f32 v216, v46, v47
	v_cvt_pk_bf16_f32 v217, v48, v49
	v_add_f32_e32 v105, v105, v180
	s_waitcnt lgkmcnt(0)
.Lfx_A_skip:
	s_cmp_lg_u32 s65, 0
	s_cbranch_scc1 .Lfx_a_done
	s_add_i32 s30, s64, 2
	s_cmp_lt_u32 s30, s37
	s_cbranch_scc1 .Lfx_a_w
	s_waitcnt vmcnt(0)
	s_branch .Lfx_a_done

; template <int DV, int NMAP>
; __device__ __forceinline__ void attn_unit(LAS unsigned char* lds, const bf16_t* U, bf16_t* MIX, const float* logf, int b, int h, int qb, float lam, float slope2, const float* gn, float outscale, const int tid) {
;     ...
;         if (t + 1 < NT) { if (PER == 2) asm volatile("s_waitcnt vmcnt(2)\n\ts_barrier" ::: "memory"); else asm volatile("s_waitcnt vmcnt(4)\n\ts_barrier" ::: "memory"); }
;     ...
;             __builtin_amdgcn_sched_barrier(0);
;             if (NDB == 4) {
;                 s16x4 lo2[2][4], hh2[2][4];
; #pragma unroll
;                 for (int e = 0; e < 2; ++e)
; #pragma unroll
;                     for (int s = 0; s < 4; ++s) { lo2[e][s] = vtr(Vb + (2 + e) * 4096 + s * 1024); hh2[e][s] = vtr(Vb + (2 + e) * 4096 + s * 1024 + 512); }
;                 __builtin_amdgcn_sched_barrier(0);
; #pragma unroll
;                 for (int s = 0; s < 4; ++s)
; #pragma unroll
;                     for (int e = 0; e < 2; ++e) {
;                         const bf16x8 vf = (bf16x8){lo[e][s][0], lo[e][s][1], lo[e][s][2], lo[e][s][3], hh[e][s][0], hh[e][s][1], hh[e][s][2], hh[e][s][3]};
;                         o[e] = __builtin_amdgcn_mfma_f32_32x32x16_bf16(vf, pk[s], o[e], 0, 0, 0);
;                     }
;                 __builtin_amdgcn_sched_barrier(0);
; #pragma unroll
;                 for (int s = 0; s < 4; ++s)
; #pragma unroll
;                     for (int e = 0; e < 2; ++e) {
;                         const bf16x8 vf = (bf16x8){lo2[e][s][0], lo2[e][s][1], lo2[e][s][2], lo2[e][s][3], hh2[e][s][0], hh2[e][s][1], hh2[e][s][2], hh2[e][s][3]};
;                         o[NDB - 2 + e] = __builtin_amdgcn_mfma_f32_32x32x16_bf16(vf, pk[s], o[NDB - 2 + e], 0, 0, 0);
;                     }
;             } else {
; #pragma unroll
;                 for (int s = 0; s < 4; ++s)
; #pragma unroll
;                     for (int e = 0; e < 2; ++e) {
;                         const bf16x8 vf = (bf16x8){lo[e][s][0], lo[e][s][1], lo[e][s][2], lo[e][s][3], hh[e][s][0], hh[e][s][1], hh[e][s][2], hh[e][s][3]};
;                         o[e] = __builtin_amdgcn_mfma_f32_32x32x16_bf16(vf, pk[s], o[e], 0, 0, 0);
;                     }
;             }
;             __builtin_amdgcn_sched_barrier(0);
;         }
;         st = (st == 2) ? 0 : st + 1; st2 = (st2 == 2) ? 0 : st2 + 1;
.Lfx_a_done:
	s_barrier
	s_add_i32 s30, s64, 3
	s_cmp_ge_u32 s30, s37
	s_cbranch_scc1 .Lfx_nodma
	s_and_b32 s30, s30, 3
	s_mul_i32 s31, s30, 0x2100
	s_add_i32 s31, s31, s20
	s_mov_b32 m0, s31
	s_lshl_b32 s30, s30, 13
	global_load_lds_dwordx4 v[102:103], off
	s_add_i32 s30, s30, s40
	s_mov_b32 m0, s30
	v_lshl_add_u64 v[102:103], v[102:103], 0, s[28:29]
	global_load_lds_dwordx4 v[100:101], off
	v_lshl_add_u64 v[100:101], v[100:101], 0, s[28:29]
.Lfx_nodma:
	s_cmp_gt_u32 s64, s66
	s_cbranch_scc1 .Lfx_B_end
	s_cmp_ge_u32 s64, s66
	s_cbranch_scc1 .Lfx_B_last
	v_add_u32_e32 v106, 0x100, v106
	s_add_i32 s30, s64, 1
	s_and_b32 s30, s30, 3
	s_mul_i32 s30, s30, 0x2100
	v_add_u32_e32 v107, s30, v244
	ds_read_b128 v[50:53], v106
	ds_read_b128 v[54:57], v106 offset:32
	ds_read_b128 v[58:61], v106 offset:64
	ds_read_b128 v[62:65], v106 offset:96
	ds_read_b128 v[34:37], v106 offset:128
	ds_read_b128 v[38:41], v106 offset:160
	ds_read_b128 v[42:45], v106 offset:192
	ds_read_b128 v[46:49], v106 offset:224
	ds_read_b128 v[82:85], v107 offset:8448
	ds_read_b128 v[86:89], v107 offset:12672
	ds_read_b128 v[90:93], v107 offset:8704
	ds_read_b128 v[94:97], v107 offset:12928
	ds_read_b128 v[108:111], v107 offset:8960
	ds_read_b128 v[112:115], v107 offset:13184
	ds_read_b128 v[116:119], v107 offset:9216
	ds_read_b128 v[136:139], v107 offset:13440
	v_mfma_f32_32x32x16_bf16 v[2:17], v[148:151], v[202:205], v[2:17]
	v_mfma_f32_32x32x16_bf16 v[18:33], v[164:167], v[202:205], v[18:33]
	v_mfma_f32_32x32x16_bf16 v[2:17], v[152:155], v[206:209], v[2:17]
	v_mfma_f32_32x32x16_bf16 v[18:33], v[168:171], v[206:209], v[18:33]
	v_mfma_f32_32x32x16_bf16 v[2:17], v[156:159], v[210:213], v[2:17]
	v_mfma_f32_32x32x16_bf16 v[18:33], v[172:175], v[210:213], v[18:33]
	v_mfma_f32_32x32x16_bf16 v[2:17], v[160:163], v[214:217], v[2:17]
	v_mfma_f32_32x32x16_bf16 v[18:33], v[176:179], v[214:217], v[18:33]
	s_waitcnt lgkmcnt(7)
	v_mfma_f32_32x32x16_bf16 v[50:65], v[82:85], v[78:81], v[50:65]
	s_waitcnt lgkmcnt(6)
	v_mfma_f32_32x32x16_bf16 v[34:49], v[86:89], v[78:81], v[34:49]
	s_waitcnt lgkmcnt(5)
	v_mfma_f32_32x32x16_bf16 v[50:65], v[90:93], v[74:77], v[50:65]
	s_waitcnt lgkmcnt(4)
	v_mfma_f32_32x32x16_bf16 v[34:49], v[94:97], v[74:77], v[34:49]
	s_waitcnt lgkmcnt(3)
	v_mfma_f32_32x32x16_bf16 v[50:65], v[108:111], v[70:73], v[50:65]
	s_waitcnt lgkmcnt(2)
	v_mfma_f32_32x32x16_bf16 v[34:49], v[112:115], v[70:73], v[34:49]
	s_waitcnt lgkmcnt(1)
	v_mfma_f32_32x32x16_bf16 v[50:65], v[116:119], v[66:69], v[50:65]
	s_waitcnt lgkmcnt(0)
	v_mfma_f32_32x32x16_bf16 v[34:49], v[136:139], v[66:69], v[34:49]
	s_lshl_b32 s61, s64, 6
	s_addk_i32 s61, 0x7f
	s_cmp_le_i32 s61, s36
	s_cbranch_scc1 .Lfx_B_end
	v_add_u32_e32 v82, s61, v130
	v_subrev_u32_e32 v84, 31, v82
	v_subrev_u32_e32 v83, 63, v82
	v_cmp_le_i32_e32 vcc, v84, v0
	s_nop 5
	v_cndmask_b32_e32 v34, v230, v34, vcc
	v_cmp_lt_i32_e32 vcc, v83, v0
	s_nop 1
	v_cndmask_b32_e32 v51, v230, v51, vcc
	v_cmp_le_i32_e32 vcc, v83, v0
	v_subrev_u32_e32 v83, 30, v82
	s_nop 0
	v_cndmask_b32_e32 v50, v230, v50, vcc
	v_cmp_le_i32_e32 vcc, v83, v0
	v_subrev_u32_e32 v83, 61, v82
	s_nop 0
	v_cndmask_b32_e32 v35, v230, v35, vcc
	v_cmp_le_i32_e32 vcc, v83, v0
	v_subrev_u32_e32 v83, 29, v82
	s_nop 0
	v_cndmask_b32_e32 v52, v230, v52, vcc
	v_cmp_le_i32_e32 vcc, v83, v0
	v_subrev_u32_e32 v83, 60, v82
	s_nop 0
	v_cndmask_b32_e32 v36, v230, v36, vcc
	v_cmp_le_i32_e32 vcc, v83, v0
	v_subrev_u32_e32 v83, 28, v82
	s_nop 0
	v_cndmask_b32_e32 v53, v230, v53, vcc
	v_cmp_le_i32_e32 vcc, v83, v0
	v_subrev_u32_e32 v83, 55, v82
	s_nop 0
	v_cndmask_b32_e32 v37, v230, v37, vcc
	v_cmp_le_i32_e32 vcc, v83, v0
	v_subrev_u32_e32 v83, 23, v82
	s_nop 0
	v_cndmask_b32_e32 v54, v230, v54, vcc
	v_cmp_le_i32_e32 vcc, v83, v0
	v_subrev_u32_e32 v83, 54, v82
	s_nop 0
	v_cndmask_b32_e32 v38, v230, v38, vcc
	v_cmp_le_i32_e32 vcc, v83, v0
	v_subrev_u32_e32 v83, 22, v82
	s_nop 0
	v_cndmask_b32_e32 v55, v230, v55, vcc
	v_cmp_le_i32_e32 vcc, v83, v0
	v_subrev_u32_e32 v83, 53, v82
	s_nop 0
	v_cndmask_b32_e32 v39, v230, v39, vcc
	v_cmp_le_i32_e32 vcc, v83, v0
	v_subrev_u32_e32 v83, 21, v82
	s_nop 0
	v_cndmask_b32_e32 v56, v230, v56, vcc
	v_cmp_le_i32_e32 vcc, v83, v0
	v_subrev_u32_e32 v83, 52, v82
	s_nop 0
	v_cndmask_b32_e32 v40, v230, v40, vcc
	v_cmp_le_i32_e32 vcc, v83, v0
	v_subrev_u32_e32 v83, 20, v82
	s_nop 0
	v_cndmask_b32_e32 v57, v230, v57, vcc
	v_cmp_le_i32_e32 vcc, v83, v0
	v_subrev_u32_e32 v83, 47, v82
	s_nop 0
	v_cndmask_b32_e32 v41, v230, v41, vcc
	v_cmp_le_i32_e32 vcc, v83, v0
	v_add_u32_e32 v83, -15, v82
	s_nop 0
	v_cndmask_b32_e32 v58, v230, v58, vcc
	v_cmp_le_i32_e32 vcc, v83, v0
	v_subrev_u32_e32 v83, 46, v82
	s_nop 0
	v_cndmask_b32_e32 v42, v230, v42, vcc
	v_cmp_le_i32_e32 vcc, v83, v0
	v_add_u32_e32 v83, -14, v82
	s_nop 0
	v_cndmask_b32_e32 v59, v230, v59, vcc
	v_cmp_le_i32_e32 vcc, v83, v0
	v_subrev_u32_e32 v83, 45, v82
	s_nop 0
	v_cndmask_b32_e32 v43, v230, v43, vcc
	v_cmp_le_i32_e32 vcc, v83, v0
	v_add_u32_e32 v83, -13, v82
	s_nop 0
	v_cndmask_b32_e32 v60, v230, v60, vcc
	v_cmp_le_i32_e32 vcc, v83, v0
	v_subrev_u32_e32 v83, 44, v82
	s_nop 0
	v_cndmask_b32_e32 v44, v230, v44, vcc
	v_cmp_le_i32_e32 vcc, v83, v0
	v_add_u32_e32 v83, -12, v82
	s_nop 0
	v_cndmask_b32_e32 v61, v230, v61, vcc
	v_cmp_le_i32_e32 vcc, v83, v0
	v_subrev_u32_e32 v83, 39, v82
	s_nop 0
	v_cndmask_b32_e32 v45, v230, v45, vcc
	v_cmp_le_i32_e32 vcc, v83, v0
	v_add_u32_e32 v83, -7, v82
	s_nop 0
	v_cndmask_b32_e32 v62, v230, v62, vcc
	v_cmp_le_i32_e32 vcc, v83, v0
	v_subrev_u32_e32 v83, 38, v82
	s_nop 0
	v_cndmask_b32_e32 v46, v230, v46, vcc
	v_cmp_le_i32_e32 vcc, v83, v0
	v_add_u32_e32 v83, -6, v82
	s_nop 0
	v_cndmask_b32_e32 v63, v230, v63, vcc
	v_cmp_le_i32_e32 vcc, v83, v0
	v_subrev_u32_e32 v83, 37, v82
	s_nop 0
	v_cndmask_b32_e32 v47, v230, v47, vcc
	v_cmp_le_i32_e32 vcc, v83, v0
	v_add_u32_e32 v83, -5, v82
	s_nop 0
	v_cndmask_b32_e32 v64, v230, v64, vcc
	v_cmp_le_i32_e32 vcc, v83, v0
	v_subrev_u32_e32 v83, 36, v82
	v_add_u32_e32 v82, -4, v82
	v_cndmask_b32_e32 v48, v230, v48, vcc
	v_cmp_le_i32_e32 vcc, v83, v0
	s_nop 1
	v_cndmask_b32_e32 v65, v230, v65, vcc
	v_cmp_le_i32_e32 vcc, v82, v0
	s_nop 1
	v_cndmask_b32_e32 v49, v230, v49, vcc
	s_branch .Lfx_B_end
.Lfx_B_last:
	v_mfma_f32_32x32x16_bf16 v[2:17], v[148:151], v[202:205], v[2:17]
	v_mfma_f32_32x32x16_bf16 v[18:33], v[164:167], v[202:205], v[18:33]
	v_mfma_f32_32x32x16_bf16 v[2:17], v[152:155], v[206:209], v[2:17]
	v_mfma_f32_32x32x16_bf16 v[18:33], v[168:171], v[206:209], v[18:33]
	v_mfma_f32_32x32x16_bf16 v[2:17], v[156:159], v[210:213], v[2:17]
	v_mfma_f32_32x32x16_bf16 v[18:33], v[172:175], v[210:213], v[18:33]
	v_mfma_f32_32x32x16_bf16 v[2:17], v[160:163], v[214:217], v[2:17]
	v_mfma_f32_32x32x16_bf16 v[18:33], v[176:179], v[214:217], v[18:33]
.Lfx_B_end:
	s_cmp_eq_u32 s65, 0
	s_cbranch_scc1 .Lfx_bL_done
	s_add_i32 s30, s64, 3
	s_cmp_lt_u32 s30, s37
	s_cbranch_scc1 .Lfx_bL_w
	s_waitcnt vmcnt(0)
	s_branch .Lfx_bL_done

; template <int DV, int NMAP>
; __device__ __forceinline__ void attn_unit(LAS unsigned char* lds, const bf16_t* U, bf16_t* MIX, const float* logf, int b, int h, int qb, float lam, float slope2, const float* gn, float outscale, const int tid) {
;     ...
;     for (int t = 0; t < NT; ++t) {
;         if (t + 1 < NT) { if (PER == 2) asm volatile("s_waitcnt vmcnt(2)\n\ts_barrier" ::: "memory"); else asm volatile("s_waitcnt vmcnt(4)\n\ts_barrier" ::: "memory"); }
;         else asm volatile("s_waitcnt vmcnt(0)\n\ts_barrier" ::: "memory");
;         if (t + 2 < NT) AT_DMA(t + 2, st2);
;     ...
;         st = (st == 2) ? 0 : st + 1; st2 = (st2 == 2) ? 0 : st2 + 1;
;     }
;     ...
;     __syncthreads();
.Lfx_bL_done:
	s_barrier
	s_add_i32 s64, s64, 1
	s_cmp_lt_u32 s64, s37
	s_cbranch_scc1 .Lfx_loop
	s_cmp_lg_u32 s65, 0
	s_cbranch_scc1 .Lfx_done
	s_barrier
.Lfx_done:
	s_mov_b32 m0, s67

; template <int DV, int NMAP>
; __device__ __forceinline__ void attn_unit(LAS unsigned char* lds, const bf16_t* U, bf16_t* MIX, const float* logf, int b, int h, int qb, float lam, float slope2, const float* gn, float outscale, const int tid) {
;     ...
;     bf16x8 qr[4];
;     {
;         const bf16_t* qp = U + (rowbase + qrow0 + r32) * UW + qcol + map * 64 + hi * 8;
; #pragma unroll
;         for (int d0 = 0; d0 < 4; ++d0) qr[d0] = *(const bf16x8*)(qp + 16 * d0);
;     }
;     asm volatile("" : "+v"(qr[0]), "+v"(qr[1]), "+v"(qr[2]), "+v"(qr[3]));
;     const bf16_t* kg = U + (rowbase + lane) * UW + kcol + wid * 8;
;     const bf16_t* vg = U + (rowbase + 16 * (wid & 3) + (lane >> 2)) * UW + vcol + (wid >> 2) * 32 + (lane & 3) * 8;
;     const unsigned ldsb = (unsigned)(size_t)lds;
;     ...
;     __syncthreads();
;     AT_DMA(0, 0);
;     if (NT > 1) AT_DMA(1, 1);
.LBB0_217:
	s_or_b64 exec, exec, s[30:31]
	s_ashr_i32 s36, s33, 6
	s_and_b32 s61, s36, 3
	s_lshl_b32 s27, s27, 9
	s_lshl_b32 s30, s61, 5
	s_and_b32 s37, s27, 0x3800
	s_or_b32 s62, s30, s62
	v_or_b32_e32 v0, s37, v122
	v_or_b32_e32 v147, s62, v0
	v_mov_b64_e32 v[2:3], s[84:85]
	s_ashr_i32 s60, s33, 8
	v_mad_u64_u32 v[2:3], s[30:31], v147, s87, v[2:3]
	s_lshl_b32 s27, s20, 7
	s_lshl_b32 s20, s20, 8
	s_lshl_b32 s30, s60, 6
	v_lshl_add_u64 v[2:3], v[2:3], 0, s[20:21]
	s_ashr_i32 s31, s30, 31
	v_lshl_add_u64 v[2:3], s[30:31], 1, v[2:3]
	v_lshlrev_b32_e32 v0, 1, v126
	v_lshl_add_u64 v[2:3], v[2:3], 0, v[0:1]
	global_load_dwordx4 v[98:101], v[2:3], off offset:3168
	global_load_dwordx4 v[102:105], v[2:3], off offset:3136
	global_load_dwordx4 v[106:109], v[2:3], off offset:3104
	global_load_dwordx4 v[110:113], v[2:3], off offset:3072
	v_or_b32_e32 v0, s37, v123
	v_mul_u32_u24_e32 v0, 0xc00, v0
	v_lshlrev_b32_e32 v0, 1, v0
	s_lshl_b32 s30, s36, 3
	v_lshl_add_u64 v[2:3], s[84:85], 0, v[0:1]
	s_ashr_i32 s31, s30, 31
	v_lshl_add_u64 v[2:3], v[2:3], 0, s[20:21]
	s_lshl_b64 s[40:41], s[30:31], 1
	s_mul_i32 s65, s36, 0x420
	v_lshl_add_u64 v[4:5], v[2:3], 0, s[40:41]
	v_lshl_or_b32 v2, s61, 4, v127
	s_add_i32 s67, s65, 0
	v_lshl_add_u64 v[6:7], v[4:5], 0, s[22:23]
	v_or_b32_e32 v2, s37, v2
	s_add_i32 s64, s67, 0x2100
	v_mul_u32_u24_e32 v2, 0xc00, v2
	v_lshlrev_b32_e32 v2, 1, v2
	v_mov_b32_e32 v3, v1
	s_lshl_b32 s30, s60, 5
	v_lshl_add_u64 v[8:9], s[84:85], 0, v[2:3]
	s_ashr_i32 s31, s30, 31
	v_lshl_add_u64 v[8:9], v[8:9], 0, s[20:21]
	s_lshr_b32 s63, s63, 6
	v_or_b32_e32 v148, s62, v122
	v_mov_b32_e32 v14, v1
	v_mov_b32_e32 v15, v1
	v_mov_b32_e32 v10, v1
	v_mov_b32_e32 v11, v1
	v_mov_b32_e32 v12, v1
	v_mov_b32_e32 v13, v1
	v_mov_b32_e32 v150, 0
	v_mov_b32_e32 v151, v142
	s_waitcnt vmcnt(0)
	s_waitcnt lgkmcnt(0)
	s_barrier
	s_mov_b32 s41, m0
	s_mov_b32 s68, s36
	s_or_b32 s40, s62, 31
	s_lshr_b32 s40, s40, 6
	s_mov_b32 s37, 0
	v_mov_b64_e32 v[118:119], v[6:7]
	s_lshl_b32 s30, s60, 6
	s_mov_b32 s31, 0
	v_lshl_add_u64 v[138:139], v[8:9], 0, s[30:31]
	v_lshlrev_b32_e32 v116, 1, v128
	v_mov_b32_e32 v117, 0
	v_lshl_add_u64 v[138:139], v[138:139], 0, v[116:117]
	s_mov_b64 s[30:31], 0x1400
	v_lshl_add_u64 v[138:139], v[138:139], 0, s[30:31]
	v_and_b32_e32 v180, 7, v123
	v_sub_u32_e32 v180, v180, v123
	s_lshl_b32 s30, s68, 3
	v_add_u32_e32 v180, s30, v180
	v_mul_i32_i24_e32 v180, 0x1800, v180
	v_lshrrev_b32_e32 v181, 3, v123
	v_subrev_u32_e32 v181, s68, v181
	v_lshl_add_u32 v180, v181, 4, v180
	v_ashrrev_i32_e32 v181, 31, v180
	v_lshl_add_u64 v[136:137], v[118:119], 0, v[180:181]
	v_bfe_u32 v180, v123, 2, 3
	v_lshrrev_b32_e32 v181, 2, v123
	v_sub_u32_e32 v180, v180, v181
	s_and_b32 s31, s68, 3
	s_lshl_b32 s31, s31, 4
	s_lshl_b32 s30, s68, 3
	s_sub_i32 s30, s30, s31
	v_add_u32_e32 v180, s30, v180
	v_mul_i32_i24_e32 v180, 0x1800, v180
	v_lshrrev_b32_e32 v181, 5, v123
	s_lshr_b32 s31, s68, 2
	v_subrev_u32_e32 v181, s31, v181
	v_lshl_add_u32 v180, v181, 6, v180
	v_ashrrev_i32_e32 v181, 31, v180
	v_lshl_add_u64 v[138:139], v[138:139], 0, v[180:181]
	s_lshr_b32 s30, s68, 2
	s_mul_i32 s30, s30, 0x1080
	s_and_b32 s31, s68, 3
	s_lshl_b32 s31, s31, 10
	s_add_i32 s30, s30, s31
	s_bfe_u32 s31, s68, 0x10001
	s_lshl_b32 s31, s31, 7
	s_add_i32 s30, s30, s31
	s_add_i32 s64, s30, 0x2100
	s_mul_i32 s30, s68, 0x800
	s_add_i32 s66, s30, 0x12900
	v_lshrrev_b32_e32 v180, 3, v122
	v_lshlrev_b32_e32 v180, 10, v180
	v_bfe_u32 v181, v122, 4, 1
	v_lshl_add_u32 v180, v181, 7, v180
	v_lshrrev_b32_e32 v181, 5, v123
	v_lshl_add_u32 v180, v181, 7, v180
	v_and_b32_e32 v181, 7, v122
	v_lshl_add_u32 v244, v181, 4, v180
	v_lshl_add_u32 v121, v148, 2, 0
	s_mov_b32 s31, s64
	s_mov_b32 s20, s66
	s_mov_b32 m0, s31
	v_lshl_add_u64 v[116:117], v[136:137], 0, s[24:25]
	global_load_lds_dwordx4 v[136:137], off
	s_add_i32 m0, s31, 0x2100
	v_lshl_add_u64 v[136:137], v[136:137], 0, s[28:29]
	global_load_lds_dwordx4 v[116:117], off
	s_mov_b32 m0, s20
	v_lshl_add_u64 v[116:117], v[138:139], 0, s[24:25]
	global_load_lds_dwordx4 v[138:139], off
	s_add_i32 m0, s20, 0x400
	v_lshl_add_u64 v[138:139], v[138:139], 0, s[28:29]
	global_load_lds_dwordx4 v[116:117], off
	s_add_i32 s31, s64, 0x4200
	s_add_i32 s20, s66, 0x4000
	s_mov_b32 m0, s31
	v_lshl_add_u64 v[116:117], v[136:137], 0, s[24:25]
	global_load_lds_dwordx4 v[136:137], off
	s_add_i32 m0, s31, 0x2100
	v_lshl_add_u64 v[136:137], v[136:137], 0, s[28:29]
	global_load_lds_dwordx4 v[116:117], off
	s_mov_b32 m0, s20
	v_lshl_add_u64 v[116:117], v[138:139], 0, s[24:25]
	global_load_lds_dwordx4 v[138:139], off
	s_add_i32 m0, s20, 0x400
	v_lshl_add_u64 v[138:139], v[138:139], 0, s[28:29]
	global_load_lds_dwordx4 v[116:117], off
	s_cmp_lt_u32 s63, 3
	s_cbranch_scc1 .Ldf_pro2
	s_add_i32 s31, s64, 0x8400
	s_add_i32 s20, s66, 0x8000
	s_mov_b32 m0, s31
	v_lshl_add_u64 v[116:117], v[136:137], 0, s[24:25]
	global_load_lds_dwordx4 v[136:137], off
	s_add_i32 m0, s31, 0x2100
	v_lshl_add_u64 v[136:137], v[136:137], 0, s[28:29]
	global_load_lds_dwordx4 v[116:117], off
	s_mov_b32 m0, s20
	v_lshl_add_u64 v[116:117], v[138:139], 0, s[24:25]
	global_load_lds_dwordx4 v[138:139], off
	s_add_i32 m0, s20, 0x400
	v_lshl_add_u64 v[138:139], v[138:139], 0, s[28:29]
	global_load_lds_dwordx4 v[116:117], off
; template <int DV, int NMAP>
; __device__ __forceinline__ void attn_unit(LAS unsigned char* lds, const bf16_t* U, bf16_t* MIX, const float* logf, int b, int h, int qb, float lam, float slope2, const float* gn, float outscale, const int tid) {
;     ...
;     const float m_run = bias[qrow0 + r32];
;     float l_run = 0.f;
;     f32x16 o[NDB];
; #pragma unroll
;     for (int d = 0; d < NDB; ++d)
; #pragma unroll
;         for (int r = 0; r < 16; ++r) o[d][r] = 0.f;
;     const int vofs = (4 * hi + ((lane & 15) >> 2)) * 64 + ((lane >> 4) & 1) * 32 + (lane & 3) * 8;
;     int st = 0, st2 = 2;
;     for (int t = 0; t < NT; ++t) {
;         if (t + 1 < NT) { if (PER == 2) asm volatile("s_waitcnt vmcnt(2)\n\ts_barrier" ::: "memory"); else asm volatile("s_waitcnt vmcnt(4)\n\ts_barrier" ::: "memory"); }
;         else asm volatile("s_waitcnt vmcnt(0)\n\ts_barrier" ::: "memory");
;         if (t + 2 < NT) AT_DMA(t + 2, st2);
;         if (64 * t <= qrow0 + 31) {
;             const LAS unsigned char* Kb = lds + AT_K + (st * NMAP + map) * AT_KT + r32 * 16;
;             const LAS unsigned char* Vb = lds + AT_V + st * VT + vofs;
;             f32x16 p0, p1;
;             {
;                 const LAS float* bp = bias + 64 * t + 4 * hi;
; #pragma unroll
;                 for (int g = 0; g < 4; ++g) { const f32x4 v = *(const LAS f32x4*)(bp + 8 * g), w = *(const LAS f32x4*)(bp + 32 + 8 * g);
;                     p0[4 * g] = v[0]; p0[4 * g + 1] = v[1]; p0[4 * g + 2] = v[2]; p0[4 * g + 3] = v[3]; p1[4 * g] = w[0]; p1[4 * g + 1] = w[1]; p1[4 * g + 2] = w[2]; p1[4 * g + 3] = w[3]; }
;             }
;             {
;                 bf16x8 kf[8];
; #pragma unroll
;                 for (int d0 = 0; d0 < 4; ++d0) { kf[2 * d0] = *(const LAS bf16x8*)(Kb + (2 * d0 + hi) * 1056); kf[2 * d0 + 1] = *(const LAS bf16x8*)(Kb + (2 * d0 + hi) * 1056 + 512); }
;                 __builtin_amdgcn_sched_barrier(0);
; #pragma unroll
;                 for (int d0 = 0; d0 < 4; ++d0) {
;                     p0 = __builtin_amdgcn_mfma_f32_32x32x16_bf16(kf[2 * d0], qr[d0], p0, 0, 0, 0);
;                     p1 = __builtin_amdgcn_mfma_f32_32x32x16_bf16(kf[2 * d0 + 1], qr[d0], p1, 0, 0, 0);
;                 }
;                 __builtin_amdgcn_sched_barrier(0);
;             }
;             if (64 * t + 63 > qrow0) {
;                 const int q = qrow0 + r32, kv0 = 64 * t + 4 * hi;
; #pragma unroll
.Ldf_pro2:
	ds_read_b32 v149, v121
	v_mov_b32_e32 v2, 0
	v_mov_b32_e32 v3, 0
	v_mov_b32_e32 v4, 0
	v_mov_b32_e32 v5, 0
	v_mov_b32_e32 v6, 0
	v_mov_b32_e32 v7, 0
	v_mov_b32_e32 v8, 0
	v_mov_b32_e32 v9, 0
	v_mov_b32_e32 v10, 0
	v_mov_b32_e32 v11, 0
	v_mov_b32_e32 v12, 0
	v_mov_b32_e32 v13, 0
	v_mov_b32_e32 v14, 0
	v_mov_b32_e32 v15, 0
	v_mov_b32_e32 v16, 0
	v_mov_b32_e32 v17, 0
	v_mov_b32_e32 v18, 0
	v_mov_b32_e32 v19, 0
	v_mov_b32_e32 v20, 0
	v_mov_b32_e32 v21, 0
	v_mov_b32_e32 v22, 0
	v_mov_b32_e32 v23, 0
	v_mov_b32_e32 v24, 0
	v_mov_b32_e32 v25, 0
	v_mov_b32_e32 v26, 0
	v_mov_b32_e32 v27, 0
	v_mov_b32_e32 v28, 0
	v_mov_b32_e32 v29, 0
	v_mov_b32_e32 v30, 0
	v_mov_b32_e32 v31, 0
	v_mov_b32_e32 v32, 0
	v_mov_b32_e32 v33, 0
	v_mov_b32_e32 v34, 0
	v_mov_b32_e32 v35, 0
	v_mov_b32_e32 v36, 0
	v_mov_b32_e32 v37, 0
	v_mov_b32_e32 v38, 0
	v_mov_b32_e32 v39, 0
	v_mov_b32_e32 v40, 0
	v_mov_b32_e32 v41, 0
	v_mov_b32_e32 v42, 0
	v_mov_b32_e32 v43, 0
	v_mov_b32_e32 v44, 0
	v_mov_b32_e32 v45, 0
	v_mov_b32_e32 v46, 0
	v_mov_b32_e32 v47, 0
	v_mov_b32_e32 v48, 0
	v_mov_b32_e32 v49, 0
	v_mov_b32_e32 v50, 0
	v_mov_b32_e32 v51, 0
	v_mov_b32_e32 v52, 0
	v_mov_b32_e32 v53, 0
	v_mov_b32_e32 v54, 0
	v_mov_b32_e32 v55, 0
	v_mov_b32_e32 v56, 0
	v_mov_b32_e32 v57, 0
	v_mov_b32_e32 v58, 0
	v_mov_b32_e32 v59, 0
	v_mov_b32_e32 v60, 0
	v_mov_b32_e32 v61, 0
	v_mov_b32_e32 v62, 0
	v_mov_b32_e32 v63, 0
	v_mov_b32_e32 v64, 0
	v_mov_b32_e32 v65, 0
	s_waitcnt vmcnt(4)
	s_barrier
	s_cmp_eq_u32 s60, 0
	s_cbranch_scc1 .Ldf_P
	s_barrier
.Ldf_P:
	ds_read_b128 v[82:85], v151
	ds_read_b128 v[86:89], v151 offset:32
	ds_read_b128 v[90:93], v151 offset:64
	ds_read_b128 v[94:97], v151 offset:96
	ds_read_b128 v[66:69], v151 offset:128
	ds_read_b128 v[70:73], v151 offset:160
	ds_read_b128 v[74:77], v151 offset:192
	ds_read_b128 v[78:81], v151 offset:224
	s_mov_b32 s30, 0
	s_and_b32 s30, s30, 3
	s_lshl_b32 s30, s30, 1
	s_add_i32 s30, s30, s60
	s_mulk_i32 s30, 0x2100
	v_add_u32_e32 v118, s30, v244
	ds_read_b128 v[168:171], v118 offset:8448
	ds_read_b128 v[172:175], v118 offset:12672
	ds_read_b128 v[176:179], v118 offset:8704
	ds_read_b128 v[190:193], v118 offset:12928
	ds_read_b128 v[194:197], v118 offset:8960
	ds_read_b128 v[198:201], v118 offset:13184
	ds_read_b128 v[234:237], v118 offset:9216
	ds_read_b128 v[238:241], v118 offset:13440
	s_waitcnt lgkmcnt(6)
	v_mfma_f32_32x32x16_bf16 v[82:97], v[168:171], v[110:113], v[82:97]
	v_mfma_f32_32x32x16_bf16 v[66:81], v[172:175], v[110:113], v[66:81]
	s_waitcnt lgkmcnt(4)
	v_mfma_f32_32x32x16_bf16 v[82:97], v[176:179], v[106:109], v[82:97]
	v_mfma_f32_32x32x16_bf16 v[66:81], v[190:193], v[106:109], v[66:81]
	s_waitcnt lgkmcnt(2)
	v_mfma_f32_32x32x16_bf16 v[82:97], v[194:197], v[102:105], v[82:97]
	v_mfma_f32_32x32x16_bf16 v[66:81], v[198:201], v[102:105], v[66:81]
	s_waitcnt lgkmcnt(0)
	v_mfma_f32_32x32x16_bf16 v[82:97], v[234:237], v[98:101], v[82:97]
	v_mfma_f32_32x32x16_bf16 v[66:81], v[238:241], v[98:101], v[66:81]
	s_movk_i32 s36, 63
	s_cmp_le_u32 s36, s62
	s_cbranch_scc1 .Ldf_P_nomask
	v_add_u32_e32 v0, s36, v130
	v_subrev_u32_e32 v115, 31, v0
	v_subrev_u32_e32 v114, 63, v0
	v_cmp_le_u32_e32 vcc, v115, v148
	s_nop 5
	v_cndmask_b32_e32 v66, v230, v66, vcc
	v_cmp_lt_u32_e32 vcc, v114, v148
	s_nop 1
	v_cndmask_b32_e32 v83, v230, v83, vcc
	v_cmp_le_u32_e32 vcc, v114, v148
	v_subrev_u32_e32 v114, 30, v0
	s_nop 0
	v_cndmask_b32_e32 v82, v230, v82, vcc
	v_cmp_le_u32_e32 vcc, v114, v148
	v_subrev_u32_e32 v114, 61, v0
	s_nop 0
	v_cndmask_b32_e32 v67, v230, v67, vcc
	v_cmp_le_u32_e32 vcc, v114, v148
	v_subrev_u32_e32 v114, 29, v0
	s_nop 0
	v_cndmask_b32_e32 v84, v230, v84, vcc
	v_cmp_le_u32_e32 vcc, v114, v148
	v_subrev_u32_e32 v114, 60, v0
	s_nop 0
	v_cndmask_b32_e32 v68, v230, v68, vcc
	v_cmp_le_u32_e32 vcc, v114, v148
	v_subrev_u32_e32 v114, 28, v0
	s_nop 0
	v_cndmask_b32_e32 v85, v230, v85, vcc
	v_cmp_le_u32_e32 vcc, v114, v148
	v_subrev_u32_e32 v114, 55, v0
	s_nop 0
	v_cndmask_b32_e32 v69, v230, v69, vcc
	v_cmp_le_u32_e32 vcc, v114, v148
	v_subrev_u32_e32 v114, 23, v0
	s_nop 0
	v_cndmask_b32_e32 v86, v230, v86, vcc
	v_cmp_le_u32_e32 vcc, v114, v148
	v_subrev_u32_e32 v114, 54, v0
	s_nop 0
	v_cndmask_b32_e32 v70, v230, v70, vcc
	v_cmp_le_u32_e32 vcc, v114, v148
	v_subrev_u32_e32 v114, 22, v0
	s_nop 0
	v_cndmask_b32_e32 v87, v230, v87, vcc
	v_cmp_le_u32_e32 vcc, v114, v148
	v_subrev_u32_e32 v114, 53, v0
	s_nop 0
	v_cndmask_b32_e32 v71, v230, v71, vcc
	v_cmp_le_u32_e32 vcc, v114, v148
	v_subrev_u32_e32 v114, 21, v0
	s_nop 0
	v_cndmask_b32_e32 v88, v230, v88, vcc
	v_cmp_le_u32_e32 vcc, v114, v148
	v_subrev_u32_e32 v114, 52, v0
	s_nop 0
	v_cndmask_b32_e32 v72, v230, v72, vcc
	v_cmp_le_u32_e32 vcc, v114, v148
	v_subrev_u32_e32 v114, 20, v0
	s_nop 0
	v_cndmask_b32_e32 v89, v230, v89, vcc
	v_cmp_le_u32_e32 vcc, v114, v148
	v_subrev_u32_e32 v114, 47, v0
	s_nop 0
	v_cndmask_b32_e32 v73, v230, v73, vcc
	v_cmp_le_u32_e32 vcc, v114, v148
	v_add_u32_e32 v114, -15, v0
	s_nop 0
	v_cndmask_b32_e32 v90, v230, v90, vcc
	v_cmp_le_u32_e32 vcc, v114, v148
	v_subrev_u32_e32 v114, 46, v0
	s_nop 0
	v_cndmask_b32_e32 v74, v230, v74, vcc
	v_cmp_le_u32_e32 vcc, v114, v148
	v_add_u32_e32 v114, -14, v0
	s_nop 0
	v_cndmask_b32_e32 v91, v230, v91, vcc
	v_cmp_le_u32_e32 vcc, v114, v148
	v_subrev_u32_e32 v114, 45, v0
	s_nop 0
	v_cndmask_b32_e32 v75, v230, v75, vcc
	v_cmp_le_u32_e32 vcc, v114, v148
	v_add_u32_e32 v114, -13, v0
	s_nop 0
	v_cndmask_b32_e32 v92, v230, v92, vcc
	v_cmp_le_u32_e32 vcc, v114, v148
	v_subrev_u32_e32 v114, 44, v0
	s_nop 0
	v_cndmask_b32_e32 v76, v230, v76, vcc
	v_cmp_le_u32_e32 vcc, v114, v148
	v_add_u32_e32 v114, -12, v0
	s_nop 0
	v_cndmask_b32_e32 v93, v230, v93, vcc
	v_cmp_le_u32_e32 vcc, v114, v148
	v_subrev_u32_e32 v114, 39, v0
	s_nop 0
	v_cndmask_b32_e32 v77, v230, v77, vcc
	v_cmp_le_u32_e32 vcc, v114, v148
	v_add_u32_e32 v114, -7, v0
	s_nop 0
	v_cndmask_b32_e32 v94, v230, v94, vcc
	v_cmp_le_u32_e32 vcc, v114, v148
	v_subrev_u32_e32 v114, 38, v0
	s_nop 0
	v_cndmask_b32_e32 v78, v230, v78, vcc
	v_cmp_le_u32_e32 vcc, v114, v148
	v_add_u32_e32 v114, -6, v0
	s_nop 0
	v_cndmask_b32_e32 v95, v230, v95, vcc
	v_cmp_le_u32_e32 vcc, v114, v148
	v_subrev_u32_e32 v114, 37, v0
	s_nop 0
	v_cndmask_b32_e32 v79, v230, v79, vcc
	v_cmp_le_u32_e32 vcc, v114, v148
	v_add_u32_e32 v114, -5, v0
	s_nop 0
	v_cndmask_b32_e32 v96, v230, v96, vcc
	v_cmp_le_u32_e32 vcc, v114, v148
	v_subrev_u32_e32 v114, 36, v0
	v_add_u32_e32 v0, -4, v0
	v_cndmask_b32_e32 v80, v230, v80, vcc
	v_cmp_le_u32_e32 vcc, v114, v148
	s_nop 1
	v_cndmask_b32_e32 v97, v230, v97, vcc
	v_cmp_le_u32_e32 vcc, v0, v148
	s_nop 1
	v_cndmask_b32_e32 v81, v230, v81, vcc
; __device__ __forceinline__ unsigned pk_bf16(float lo, float hi) { return pg8::cvt_pk_bf16(lo, hi); }
; __device__ __forceinline__ s16x4 vtr(const LAS unsigned char* p) { typedef short v4i16_t __attribute__((ext_vector_type(4))); return __builtin_bit_cast(s16x4, __builtin_amdgcn_ds_read_tr16_b64_v4i16((LAS v4i16_t*)p)); }
; template <int DV, int NMAP>
; __device__ __forceinline__ void attn_unit(LAS unsigned char* lds, const bf16_t* U, bf16_t* MIX, const float* logf, int b, int h, int qb, float lam, float slope2, const float* gn, float outscale, const int tid) {
;     ...
;             s16x4 lo[2][4], hh[2][4];
; #pragma unroll
;             for (int e = 0; e < 2; ++e)
; #pragma unroll
;                 for (int s = 0; s < 4; ++s) { lo[e][s] = vtr(Vb + e * 4096 + s * 1024); hh[e][s] = vtr(Vb + e * 4096 + s * 1024 + 512); }
;             __builtin_amdgcn_sched_barrier(0);
;             {
;                 float s0 = 0.f, s1 = 0.f, s2 = 0.f, s3 = 0.f;
; #pragma unroll
;                 for (int r = 0; r < 16; r += 2) { p0[r] = __builtin_amdgcn_exp2f(p0[r] - m_run); p0[r + 1] = __builtin_amdgcn_exp2f(p0[r + 1] - m_run); p1[r] = __builtin_amdgcn_exp2f(p1[r] - m_run); p1[r + 1] = __builtin_amdgcn_exp2f(p1[r + 1] - m_run);
;                     s0 += p0[r]; s1 += p0[r + 1]; s2 += p1[r]; s3 += p1[r + 1]; }
;                 l_run += (s0 + s1) + (s2 + s3);
;             }
;             bf16x8 pk[4];
;             {
;                 u32x4 w;
;                 w.x = pk_bf16(p0[0], p0[1]); w.y = pk_bf16(p0[2], p0[3]); w.z = pk_bf16(p0[4], p0[5]); w.w = pk_bf16(p0[6], p0[7]); pk[0] = __builtin_bit_cast(bf16x8, w);
;                 w.x = pk_bf16(p0[8], p0[9]); w.y = pk_bf16(p0[10], p0[11]); w.z = pk_bf16(p0[12], p0[13]); w.w = pk_bf16(p0[14], p0[15]); pk[1] = __builtin_bit_cast(bf16x8, w);
;                 w.x = pk_bf16(p1[0], p1[1]); w.y = pk_bf16(p1[2], p1[3]); w.z = pk_bf16(p1[4], p1[5]); w.w = pk_bf16(p1[6], p1[7]); pk[2] = __builtin_bit_cast(bf16x8, w);
;                 w.x = pk_bf16(p1[8], p1[9]); w.y = pk_bf16(p1[10], p1[11]); w.z = pk_bf16(p1[12], p1[13]); w.w = pk_bf16(p1[14], p1[15]); pk[3] = __builtin_bit_cast(bf16x8, w);
;             }
.Ldf_P_nomask:
	s_cmp_eq_u32 s60, 0
	s_cbranch_scc1 .Ldf_bP_done
	s_cmp_gt_u32 s63, 2
	s_cbranch_scc1 .Ldf_bP_w
	s_waitcnt vmcnt(0)
	s_branch .Ldf_bP_done
.Ldf_bP_w:
	s_waitcnt vmcnt(4)
.Ldf_bP_done:
	s_barrier
.Ldf_loop:
	s_cmp_gt_u32 s37, s40
	s_cbranch_scc1 .Ldf_A_skip
	s_and_b32 s30, s37, 3
	s_lshl_b32 s30, s30, 14
	s_add_i32 s30, s30, 0x12900
	v_add_u32_e32 v119, s30, v141
	ds_read_b64_tr_b16 v[152:153], v119
	ds_read_b64_tr_b16 v[154:155], v119 offset:2048
	ds_read_b64_tr_b16 v[156:157], v119 offset:4096
	ds_read_b64_tr_b16 v[158:159], v119 offset:6144
	ds_read_b64_tr_b16 v[160:161], v119 offset:8192
	ds_read_b64_tr_b16 v[162:163], v119 offset:10240
	ds_read_b64_tr_b16 v[164:165], v119 offset:12288
	ds_read_b64_tr_b16 v[166:167], v119 offset:14336
	ds_read_b64_tr_b16 v[168:169], v119 offset:512
	ds_read_b64_tr_b16 v[170:171], v119 offset:2560
	ds_read_b64_tr_b16 v[172:173], v119 offset:4608
	ds_read_b64_tr_b16 v[174:175], v119 offset:6656
	ds_read_b64_tr_b16 v[176:177], v119 offset:8704
	ds_read_b64_tr_b16 v[178:179], v119 offset:10752
	ds_read_b64_tr_b16 v[190:191], v119 offset:12800
	ds_read_b64_tr_b16 v[192:193], v119 offset:14848
	ds_read_b64_tr_b16 v[194:195], v119 offset:1024
	ds_read_b64_tr_b16 v[196:197], v119 offset:3072
	ds_read_b64_tr_b16 v[198:199], v119 offset:5120
	ds_read_b64_tr_b16 v[200:201], v119 offset:7168
	ds_read_b64_tr_b16 v[234:235], v119 offset:9216
	ds_read_b64_tr_b16 v[236:237], v119 offset:11264
	ds_read_b64_tr_b16 v[238:239], v119 offset:13312
	ds_read_b64_tr_b16 v[240:241], v119 offset:15360
	v_sub_f32_e32 v82, v82, v149
	v_sub_f32_e32 v66, v66, v149
	v_sub_f32_e32 v83, v83, v149
	v_exp_f32_e32 v82, v82
	v_sub_f32_e32 v67, v67, v149
	v_exp_f32_e32 v66, v66
	v_sub_f32_e32 v84, v84, v149
	v_exp_f32_e32 v83, v83
	v_sub_f32_e32 v68, v68, v149
	v_exp_f32_e32 v67, v67
	v_sub_f32_e32 v85, v85, v149
	v_exp_f32_e32 v84, v84
	v_sub_f32_e32 v69, v69, v149
	v_exp_f32_e32 v68, v68
	v_sub_f32_e32 v86, v86, v149
	v_exp_f32_e32 v85, v85
	v_sub_f32_e32 v70, v70, v149
	v_exp_f32_e32 v69, v69
	v_sub_f32_e32 v87, v87, v149
	v_exp_f32_e32 v86, v86
	v_sub_f32_e32 v71, v71, v149
	v_exp_f32_e32 v70, v70
	v_sub_f32_e32 v88, v88, v149
	v_exp_f32_e32 v87, v87
	v_sub_f32_e32 v72, v72, v149
	v_exp_f32_e32 v71, v71
	v_sub_f32_e32 v89, v89, v149
	v_exp_f32_e32 v88, v88
	v_sub_f32_e32 v73, v73, v149
	v_exp_f32_e32 v72, v72
	v_sub_f32_e32 v90, v90, v149
	v_exp_f32_e32 v89, v89
	v_sub_f32_e32 v74, v74, v149
	v_exp_f32_e32 v73, v73
	v_sub_f32_e32 v91, v91, v149
	v_exp_f32_e32 v90, v90
	v_sub_f32_e32 v75, v75, v149
	v_exp_f32_e32 v74, v74
	v_sub_f32_e32 v92, v92, v149
	v_exp_f32_e32 v91, v91
	v_sub_f32_e32 v76, v76, v149
	v_exp_f32_e32 v75, v75
	v_sub_f32_e32 v93, v93, v149
	v_exp_f32_e32 v92, v92
	v_sub_f32_e32 v77, v77, v149
	v_exp_f32_e32 v76, v76
	v_sub_f32_e32 v94, v94, v149
	v_exp_f32_e32 v93, v93
	v_sub_f32_e32 v78, v78, v149
	v_exp_f32_e32 v77, v77
	v_sub_f32_e32 v95, v95, v149
	v_exp_f32_e32 v94, v94
	v_sub_f32_e32 v79, v79, v149
	v_exp_f32_e32 v78, v78
	v_sub_f32_e32 v96, v96, v149
	v_exp_f32_e32 v95, v95
	v_sub_f32_e32 v80, v80, v149
	v_exp_f32_e32 v79, v79
	v_sub_f32_e32 v97, v97, v149
	v_exp_f32_e32 v96, v96
	v_sub_f32_e32 v81, v81, v149
	v_exp_f32_e32 v80, v80
	v_exp_f32_e32 v97, v97
	v_exp_f32_e32 v81, v81
	s_nop 0
	v_add_f32_e32 v180, v82, v83
	v_add_f32_e32 v181, v84, v85
	v_add_f32_e32 v182, v66, v67
	v_add_f32_e32 v120, v68, v69
	v_add_f32_e32 v180, v180, v86
	v_add_f32_e32 v181, v181, v87
	v_add_f32_e32 v182, v182, v70
	v_add_f32_e32 v120, v120, v71
	v_add_f32_e32 v180, v180, v88
	v_add_f32_e32 v181, v181, v89
	v_add_f32_e32 v182, v182, v72
	v_add_f32_e32 v120, v120, v73
	v_add_f32_e32 v180, v180, v90
	v_add_f32_e32 v181, v181, v91
	v_add_f32_e32 v182, v182, v74
	v_add_f32_e32 v120, v120, v75
	v_add_f32_e32 v180, v180, v92
	v_add_f32_e32 v181, v181, v93
	v_add_f32_e32 v182, v182, v76
	v_add_f32_e32 v120, v120, v77
	v_add_f32_e32 v180, v180, v94
	v_add_f32_e32 v181, v181, v95
	v_add_f32_e32 v182, v182, v78
	v_add_f32_e32 v120, v120, v79
	v_add_f32_e32 v180, v180, v96
	v_add_f32_e32 v181, v181, v97
	v_add_f32_e32 v182, v182, v80
	v_add_f32_e32 v120, v120, v81
	v_add_f32_e32 v180, v180, v181
	v_add_f32_e32 v182, v182, v120
	v_cvt_pk_bf16_f32 v202, v82, v83
	v_cvt_pk_bf16_f32 v203, v84, v85
	v_cvt_pk_bf16_f32 v204, v86, v87
	v_cvt_pk_bf16_f32 v205, v88, v89
	v_cvt_pk_bf16_f32 v206, v90, v91
	v_cvt_pk_bf16_f32 v207, v92, v93
	v_cvt_pk_bf16_f32 v208, v94, v95
	v_cvt_pk_bf16_f32 v209, v96, v97
	v_add_f32_e32 v180, v180, v182
	v_cvt_pk_bf16_f32 v210, v66, v67
	v_cvt_pk_bf16_f32 v211, v68, v69
	v_cvt_pk_bf16_f32 v212, v70, v71
	v_cvt_pk_bf16_f32 v213, v72, v73
	v_cvt_pk_bf16_f32 v214, v74, v75
	v_cvt_pk_bf16_f32 v215, v76, v77
	v_cvt_pk_bf16_f32 v216, v78, v79
	v_cvt_pk_bf16_f32 v217, v80, v81
	v_add_f32_e32 v150, v150, v180
	s_waitcnt lgkmcnt(0)
.Ldf_A_skip:
	s_cmp_lg_u32 s60, 0
	s_cbranch_scc1 .Ldf_a_done
	s_add_i32 s30, s37, 2
	s_cmp_lt_u32 s30, s63
	s_cbranch_scc1 .Ldf_a_w
	s_waitcnt vmcnt(0)
	s_branch .Ldf_a_done

; __device__ __forceinline__ s16x4 vtr(const LAS unsigned char* p) { typedef short v4i16_t __attribute__((ext_vector_type(4))); return __builtin_bit_cast(s16x4, __builtin_amdgcn_ds_read_tr16_b64_v4i16((LAS v4i16_t*)p)); }
; template <int DV, int NMAP>
; __device__ __forceinline__ void attn_unit(LAS unsigned char* lds, const bf16_t* U, bf16_t* MIX, const float* logf, int b, int h, int qb, float lam, float slope2, const float* gn, float outscale, const int tid) {
;     ...
;         if (t + 1 < NT) { if (PER == 2) asm volatile("s_waitcnt vmcnt(2)\n\ts_barrier" ::: "memory"); else asm volatile("s_waitcnt vmcnt(4)\n\ts_barrier" ::: "memory"); }
;         else asm volatile("s_waitcnt vmcnt(0)\n\ts_barrier" ::: "memory");
;         if (t + 2 < NT) AT_DMA(t + 2, st2);
;     ...
;             __builtin_amdgcn_sched_barrier(0);
;             if (NDB == 4) {
;                 s16x4 lo2[2][4], hh2[2][4];
; #pragma unroll
;                 for (int e = 0; e < 2; ++e)
; #pragma unroll
;                     for (int s = 0; s < 4; ++s) { lo2[e][s] = vtr(Vb + (2 + e) * 4096 + s * 1024); hh2[e][s] = vtr(Vb + (2 + e) * 4096 + s * 1024 + 512); }
;                 __builtin_amdgcn_sched_barrier(0);
; #pragma unroll
;                 for (int s = 0; s < 4; ++s)
; #pragma unroll
;                     for (int e = 0; e < 2; ++e) {
;                         const bf16x8 vf = (bf16x8){lo[e][s][0], lo[e][s][1], lo[e][s][2], lo[e][s][3], hh[e][s][0], hh[e][s][1], hh[e][s][2], hh[e][s][3]};
;                         o[e] = __builtin_amdgcn_mfma_f32_32x32x16_bf16(vf, pk[s], o[e], 0, 0, 0);
;                     }
;                 __builtin_amdgcn_sched_barrier(0);
; #pragma unroll
;                 for (int s = 0; s < 4; ++s)
; #pragma unroll
;                     for (int e = 0; e < 2; ++e) {
;                         const bf16x8 vf = (bf16x8){lo2[e][s][0], lo2[e][s][1], lo2[e][s][2], lo2[e][s][3], hh2[e][s][0], hh2[e][s][1], hh2[e][s][2], hh2[e][s][3]};
;                         o[NDB - 2 + e] = __builtin_amdgcn_mfma_f32_32x32x16_bf16(vf, pk[s], o[NDB - 2 + e], 0, 0, 0);
;                     }
.Ldf_a_done:
	s_barrier
	s_add_i32 s30, s37, 3
	s_cmp_ge_u32 s30, s63
	s_cbranch_scc1 .Ldf_nodma
	s_and_b32 s30, s30, 3
	s_mul_i32 s31, s30, 0x4200
	s_add_i32 s31, s31, s64
	s_lshl_b32 s20, s30, 14
	s_add_i32 s20, s20, s66
	s_mov_b32 m0, s31
	v_lshl_add_u64 v[116:117], v[136:137], 0, s[24:25]
	global_load_lds_dwordx4 v[136:137], off
	s_add_i32 m0, s31, 0x2100
	v_lshl_add_u64 v[136:137], v[136:137], 0, s[28:29]
	global_load_lds_dwordx4 v[116:117], off
	s_mov_b32 m0, s20
	v_lshl_add_u64 v[116:117], v[138:139], 0, s[24:25]
	global_load_lds_dwordx4 v[138:139], off
	s_add_i32 m0, s20, 0x400
	v_lshl_add_u64 v[138:139], v[138:139], 0, s[28:29]
	global_load_lds_dwordx4 v[116:117], off
.Ldf_nodma:
	s_cmp_gt_u32 s37, s40
	s_cbranch_scc1 .Ldf_B_end
	s_cmp_ge_u32 s37, s40
	s_cbranch_scc1 .Ldf_B_last
	v_add_u32_e32 v151, 0x100, v151
	ds_read_b128 v[82:85], v151
	ds_read_b128 v[86:89], v151 offset:32
	ds_read_b128 v[90:93], v151 offset:64
	ds_read_b128 v[94:97], v151 offset:96
	ds_read_b128 v[66:69], v151 offset:128
	ds_read_b128 v[70:73], v151 offset:160
	ds_read_b128 v[74:77], v151 offset:192
	ds_read_b128 v[78:81], v151 offset:224
	v_mfma_f32_32x32x16_bf16 v[50:65], v[152:155], v[202:205], v[50:65]
	v_mfma_f32_32x32x16_bf16 v[50:65], v[156:159], v[206:209], v[50:65]
	v_mfma_f32_32x32x16_bf16 v[50:65], v[160:163], v[210:213], v[50:65]
	v_mfma_f32_32x32x16_bf16 v[50:65], v[164:167], v[214:217], v[50:65]
	ds_read_b64_tr_b16 v[152:153], v119 offset:1536
	ds_read_b64_tr_b16 v[154:155], v119 offset:3584
	ds_read_b64_tr_b16 v[156:157], v119 offset:5632
	ds_read_b64_tr_b16 v[158:159], v119 offset:7680
	ds_read_b64_tr_b16 v[160:161], v119 offset:9728
	ds_read_b64_tr_b16 v[162:163], v119 offset:11776
	ds_read_b64_tr_b16 v[164:165], v119 offset:13824
	ds_read_b64_tr_b16 v[166:167], v119 offset:15872
	v_mfma_f32_32x32x16_bf16 v[34:49], v[168:171], v[202:205], v[34:49]
	v_mfma_f32_32x32x16_bf16 v[34:49], v[172:175], v[206:209], v[34:49]
	v_mfma_f32_32x32x16_bf16 v[34:49], v[176:179], v[210:213], v[34:49]
	v_mfma_f32_32x32x16_bf16 v[34:49], v[190:193], v[214:217], v[34:49]
	s_add_i32 s30, s37, 1
	s_and_b32 s30, s30, 3
	s_lshl_b32 s30, s30, 1
	s_add_i32 s30, s30, s60
	s_mulk_i32 s30, 0x2100
	v_add_u32_e32 v118, s30, v244
	ds_read_b128 v[168:171], v118 offset:8448
	ds_read_b128 v[172:175], v118 offset:12672
	ds_read_b128 v[176:179], v118 offset:8704
	ds_read_b128 v[190:193], v118 offset:12928
	v_mfma_f32_32x32x16_bf16 v[18:33], v[194:197], v[202:205], v[18:33]
	v_mfma_f32_32x32x16_bf16 v[18:33], v[198:201], v[206:209], v[18:33]
	v_mfma_f32_32x32x16_bf16 v[18:33], v[234:237], v[210:213], v[18:33]
	v_mfma_f32_32x32x16_bf16 v[18:33], v[238:241], v[214:217], v[18:33]
	ds_read_b128 v[194:197], v118 offset:8960
	ds_read_b128 v[198:201], v118 offset:13184
	ds_read_b128 v[234:237], v118 offset:9216
	ds_read_b128 v[238:241], v118 offset:13440
	s_waitcnt lgkmcnt(8)
	v_mfma_f32_32x32x16_bf16 v[2:17], v[152:155], v[202:205], v[2:17]
	v_mfma_f32_32x32x16_bf16 v[2:17], v[156:159], v[206:209], v[2:17]
	v_mfma_f32_32x32x16_bf16 v[2:17], v[160:163], v[210:213], v[2:17]
	v_mfma_f32_32x32x16_bf16 v[2:17], v[164:167], v[214:217], v[2:17]
	s_waitcnt lgkmcnt(4)
	v_mfma_f32_32x32x16_bf16 v[82:97], v[168:171], v[110:113], v[82:97]
	v_mfma_f32_32x32x16_bf16 v[66:81], v[172:175], v[110:113], v[66:81]
	v_mfma_f32_32x32x16_bf16 v[82:97], v[176:179], v[106:109], v[82:97]
	v_mfma_f32_32x32x16_bf16 v[66:81], v[190:193], v[106:109], v[66:81]
	s_waitcnt lgkmcnt(0)
	v_mfma_f32_32x32x16_bf16 v[82:97], v[194:197], v[102:105], v[82:97]
	v_mfma_f32_32x32x16_bf16 v[66:81], v[198:201], v[102:105], v[66:81]
	v_mfma_f32_32x32x16_bf16 v[82:97], v[234:237], v[98:101], v[82:97]
	v_mfma_f32_32x32x16_bf16 v[66:81], v[238:241], v[98:101], v[66:81]
	s_lshl_b32 s36, s37, 6
	s_addk_i32 s36, 0x7f
	s_cmp_le_u32 s36, s62
	s_cbranch_scc1 .Ldf_B_end
; template <int DV, int NMAP>
; __device__ __forceinline__ void attn_unit(LAS unsigned char* lds, const bf16_t* U, bf16_t* MIX, const float* logf, int b, int h, int qb, float lam, float slope2, const float* gn, float outscale, const int tid) {
;     ...
;             if (64 * t + 63 > qrow0) {
;                 const int q = qrow0 + r32, kv0 = 64 * t + 4 * hi;
; #pragma unroll
;                 for (int r = 0; r < 16; ++r) { const int kv = kv0 + (r & 3) + 8 * (r >> 2); if (kv > q) p0[r] = -1e30f; if (kv + 32 > q) p1[r] = -1e30f; }
;             }
;     ...
;             if (NDB == 4) {
;                 s16x4 lo2[2][4], hh2[2][4];
; #pragma unroll
;                 for (int e = 0; e < 2; ++e)
; #pragma unroll
;                     for (int s = 0; s < 4; ++s) { lo2[e][s] = vtr(Vb + (2 + e) * 4096 + s * 1024); hh2[e][s] = vtr(Vb + (2 + e) * 4096 + s * 1024 + 512); }
;                 __builtin_amdgcn_sched_barrier(0);
; #pragma unroll
;                 for (int s = 0; s < 4; ++s)
; #pragma unroll
;                     for (int e = 0; e < 2; ++e) {
;                         const bf16x8 vf = (bf16x8){lo[e][s][0], lo[e][s][1], lo[e][s][2], lo[e][s][3], hh[e][s][0], hh[e][s][1], hh[e][s][2], hh[e][s][3]};
;                         o[e] = __builtin_amdgcn_mfma_f32_32x32x16_bf16(vf, pk[s], o[e], 0, 0, 0);
;                     }
;                 __builtin_amdgcn_sched_barrier(0);
; #pragma unroll
;                 for (int s = 0; s < 4; ++s)
; #pragma unroll
;                     for (int e = 0; e < 2; ++e) {
;                         const bf16x8 vf = (bf16x8){lo2[e][s][0], lo2[e][s][1], lo2[e][s][2], lo2[e][s][3], hh2[e][s][0], hh2[e][s][1], hh2[e][s][2], hh2[e][s][3]};
;                         o[NDB - 2 + e] = __builtin_amdgcn_mfma_f32_32x32x16_bf16(vf, pk[s], o[NDB - 2 + e], 0, 0, 0);
;                     }
;             } else {
; #pragma unroll
;                 for (int s = 0; s < 4; ++s)
; #pragma unroll
;                     for (int e = 0; e < 2; ++e) {
;                         const bf16x8 vf = (bf16x8){lo[e][s][0], lo[e][s][1], lo[e][s][2], lo[e][s][3], hh[e][s][0], hh[e][s][1], hh[e][s][2], hh[e][s][3]};
;                         o[e] = __builtin_amdgcn_mfma_f32_32x32x16_bf16(vf, pk[s], o[e], 0, 0, 0);
;                     }
;             }
;             __builtin_amdgcn_sched_barrier(0);
;         }
	v_add_u32_e32 v0, s36, v130
	v_subrev_u32_e32 v115, 31, v0
	v_subrev_u32_e32 v114, 63, v0
	v_cmp_le_u32_e32 vcc, v115, v148
	s_nop 5
	v_cndmask_b32_e32 v66, v230, v66, vcc
	v_cmp_lt_u32_e32 vcc, v114, v148
	s_nop 1
	v_cndmask_b32_e32 v83, v230, v83, vcc
	v_cmp_le_u32_e32 vcc, v114, v148
	v_subrev_u32_e32 v114, 30, v0
	s_nop 0
	v_cndmask_b32_e32 v82, v230, v82, vcc
	v_cmp_le_u32_e32 vcc, v114, v148
	v_subrev_u32_e32 v114, 61, v0
	s_nop 0
	v_cndmask_b32_e32 v67, v230, v67, vcc
	v_cmp_le_u32_e32 vcc, v114, v148
	v_subrev_u32_e32 v114, 29, v0
	s_nop 0
	v_cndmask_b32_e32 v84, v230, v84, vcc
	v_cmp_le_u32_e32 vcc, v114, v148
	v_subrev_u32_e32 v114, 60, v0
	s_nop 0
	v_cndmask_b32_e32 v68, v230, v68, vcc
	v_cmp_le_u32_e32 vcc, v114, v148
	v_subrev_u32_e32 v114, 28, v0
	s_nop 0
	v_cndmask_b32_e32 v85, v230, v85, vcc
	v_cmp_le_u32_e32 vcc, v114, v148
	v_subrev_u32_e32 v114, 55, v0
	s_nop 0
	v_cndmask_b32_e32 v69, v230, v69, vcc
	v_cmp_le_u32_e32 vcc, v114, v148
	v_subrev_u32_e32 v114, 23, v0
	s_nop 0
	v_cndmask_b32_e32 v86, v230, v86, vcc
	v_cmp_le_u32_e32 vcc, v114, v148
	v_subrev_u32_e32 v114, 54, v0
	s_nop 0
	v_cndmask_b32_e32 v70, v230, v70, vcc
	v_cmp_le_u32_e32 vcc, v114, v148
	v_subrev_u32_e32 v114, 22, v0
	s_nop 0
	v_cndmask_b32_e32 v87, v230, v87, vcc
	v_cmp_le_u32_e32 vcc, v114, v148
	v_subrev_u32_e32 v114, 53, v0
	s_nop 0
	v_cndmask_b32_e32 v71, v230, v71, vcc
	v_cmp_le_u32_e32 vcc, v114, v148
	v_subrev_u32_e32 v114, 21, v0
	s_nop 0
	v_cndmask_b32_e32 v88, v230, v88, vcc
	v_cmp_le_u32_e32 vcc, v114, v148
	v_subrev_u32_e32 v114, 52, v0
	s_nop 0
	v_cndmask_b32_e32 v72, v230, v72, vcc
	v_cmp_le_u32_e32 vcc, v114, v148
	v_subrev_u32_e32 v114, 20, v0
	s_nop 0
	v_cndmask_b32_e32 v89, v230, v89, vcc
	v_cmp_le_u32_e32 vcc, v114, v148
	v_subrev_u32_e32 v114, 47, v0
	s_nop 0
	v_cndmask_b32_e32 v73, v230, v73, vcc
	v_cmp_le_u32_e32 vcc, v114, v148
	v_add_u32_e32 v114, -15, v0
	s_nop 0
	v_cndmask_b32_e32 v90, v230, v90, vcc
	v_cmp_le_u32_e32 vcc, v114, v148
	v_subrev_u32_e32 v114, 46, v0
	s_nop 0
	v_cndmask_b32_e32 v74, v230, v74, vcc
	v_cmp_le_u32_e32 vcc, v114, v148
	v_add_u32_e32 v114, -14, v0
	s_nop 0
	v_cndmask_b32_e32 v91, v230, v91, vcc
	v_cmp_le_u32_e32 vcc, v114, v148
	v_subrev_u32_e32 v114, 45, v0
	s_nop 0
	v_cndmask_b32_e32 v75, v230, v75, vcc
	v_cmp_le_u32_e32 vcc, v114, v148
	v_add_u32_e32 v114, -13, v0
	s_nop 0
	v_cndmask_b32_e32 v92, v230, v92, vcc
	v_cmp_le_u32_e32 vcc, v114, v148
	v_subrev_u32_e32 v114, 44, v0
	s_nop 0
	v_cndmask_b32_e32 v76, v230, v76, vcc
	v_cmp_le_u32_e32 vcc, v114, v148
	v_add_u32_e32 v114, -12, v0
	s_nop 0
	v_cndmask_b32_e32 v93, v230, v93, vcc
	v_cmp_le_u32_e32 vcc, v114, v148
	v_subrev_u32_e32 v114, 39, v0
	s_nop 0
	v_cndmask_b32_e32 v77, v230, v77, vcc
	v_cmp_le_u32_e32 vcc, v114, v148
	v_add_u32_e32 v114, -7, v0
	s_nop 0
	v_cndmask_b32_e32 v94, v230, v94, vcc
	v_cmp_le_u32_e32 vcc, v114, v148
	v_subrev_u32_e32 v114, 38, v0
	s_nop 0
	v_cndmask_b32_e32 v78, v230, v78, vcc
	v_cmp_le_u32_e32 vcc, v114, v148
	v_add_u32_e32 v114, -6, v0
	s_nop 0
	v_cndmask_b32_e32 v95, v230, v95, vcc
	v_cmp_le_u32_e32 vcc, v114, v148
	v_subrev_u32_e32 v114, 37, v0
	s_nop 0
	v_cndmask_b32_e32 v79, v230, v79, vcc
	v_cmp_le_u32_e32 vcc, v114, v148
	v_add_u32_e32 v114, -5, v0
	s_nop 0
	v_cndmask_b32_e32 v96, v230, v96, vcc
	v_cmp_le_u32_e32 vcc, v114, v148
	v_subrev_u32_e32 v114, 36, v0
	v_add_u32_e32 v0, -4, v0
	v_cndmask_b32_e32 v80, v230, v80, vcc
	v_cmp_le_u32_e32 vcc, v114, v148
	s_nop 1
	v_cndmask_b32_e32 v97, v230, v97, vcc
	v_cmp_le_u32_e32 vcc, v0, v148
	s_nop 1
	v_cndmask_b32_e32 v81, v230, v81, vcc
	s_branch .Ldf_B_end
.Ldf_B_last:
	v_mfma_f32_32x32x16_bf16 v[50:65], v[152:155], v[202:205], v[50:65]
	v_mfma_f32_32x32x16_bf16 v[50:65], v[156:159], v[206:209], v[50:65]
	v_mfma_f32_32x32x16_bf16 v[50:65], v[160:163], v[210:213], v[50:65]
	v_mfma_f32_32x32x16_bf16 v[50:65], v[164:167], v[214:217], v[50:65]
	ds_read_b64_tr_b16 v[152:153], v119 offset:1536
	ds_read_b64_tr_b16 v[154:155], v119 offset:3584
	ds_read_b64_tr_b16 v[156:157], v119 offset:5632
	ds_read_b64_tr_b16 v[158:159], v119 offset:7680
	ds_read_b64_tr_b16 v[160:161], v119 offset:9728
	ds_read_b64_tr_b16 v[162:163], v119 offset:11776
	ds_read_b64_tr_b16 v[164:165], v119 offset:13824
	ds_read_b64_tr_b16 v[166:167], v119 offset:15872
	v_mfma_f32_32x32x16_bf16 v[34:49], v[168:171], v[202:205], v[34:49]
	v_mfma_f32_32x32x16_bf16 v[34:49], v[172:175], v[206:209], v[34:49]
	v_mfma_f32_32x32x16_bf16 v[34:49], v[176:179], v[210:213], v[34:49]
	v_mfma_f32_32x32x16_bf16 v[34:49], v[190:193], v[214:217], v[34:49]
	v_mfma_f32_32x32x16_bf16 v[18:33], v[194:197], v[202:205], v[18:33]
	v_mfma_f32_32x32x16_bf16 v[18:33], v[198:201], v[206:209], v[18:33]
	v_mfma_f32_32x32x16_bf16 v[18:33], v[234:237], v[210:213], v[18:33]
	v_mfma_f32_32x32x16_bf16 v[18:33], v[238:241], v[214:217], v[18:33]
	s_waitcnt lgkmcnt(0)
	v_mfma_f32_32x32x16_bf16 v[2:17], v[152:155], v[202:205], v[2:17]
	v_mfma_f32_32x32x16_bf16 v[2:17], v[156:159], v[206:209], v[2:17]
	v_mfma_f32_32x32x16_bf16 v[2:17], v[160:163], v[210:213], v[2:17]
	v_mfma_f32_32x32x16_bf16 v[2:17], v[164:167], v[214:217], v[2:17]
.Ldf_B_end:
	s_cmp_eq_u32 s60, 0
	s_cbranch_scc1 .Ldf_b_done
	s_add_i32 s30, s37, 3
	s_cmp_lt_u32 s30, s63
	s_cbranch_scc1 .Ldf_b_w
	s_waitcnt vmcnt(0)
	s_branch .Ldf_b_done

; template <int DV, int NMAP>
; __device__ __forceinline__ void attn_unit(LAS unsigned char* lds, const bf16_t* U, bf16_t* MIX, const float* logf, int b, int h, int qb, float lam, float slope2, const float* gn, float outscale, const int tid) {
;     ...
;     for (int t = 0; t < NT; ++t) {
;     ...
;         st = (st == 2) ? 0 : st + 1; st2 = (st2 == 2) ? 0 : st2 + 1;
;     }
;     ...
;     __syncthreads();
.Ldf_b_done:
	s_barrier
	s_add_i32 s37, s37, 1
	s_cmp_lt_u32 s37, s63
	s_cbranch_scc1 .Ldf_loop
	s_cmp_lg_u32 s60, 0
	s_cbranch_scc1 .Ldf_done
	s_barrier
.Ldf_done:
	s_mov_b32 m0, s41
